# v35
# speedup vs baseline: 1.0104x; 1.0019x over previous
.LBB0_932:
	v_lshl_add_u32 v144, s71, 8, v133
	s_lshl_b32 s12, s10, 8
	v_ashrrev_i32_e32 v145, 31, v144
	s_ashr_i32 s13, s12, 31
	v_lshlrev_b64 v[152:153], 11, v[144:145]
	v_mov_b32_e32 v143, s13
	v_or_b32_e32 v142, s12, v132
	v_lshl_add_u64 v[152:153], s[62:63], 0, v[152:153]
	v_lshl_add_u64 v[152:153], v[142:143], 1, v[152:153]
	global_load_dwordx2 v[164:165], v[152:153], off
	global_load_dwordx2 v[166:167], v[152:153], off offset:32
	global_load_dwordx2 v[168:169], v[152:153], off offset:256
	global_load_dwordx2 v[170:171], v[152:153], off offset:288
	v_add_co_u32_e32 v230, vcc, 0x8000, v152
	s_nop 1
	v_addc_co_u32_e32 v231, vcc, 0, v153, vcc
	global_load_dwordx2 v[172:173], v[230:231], off
	global_load_dwordx2 v[174:175], v[230:231], off offset:32
	global_load_dwordx2 v[176:177], v[230:231], off offset:256
	global_load_dwordx2 v[178:179], v[230:231], off offset:288
	v_add_co_u32_e32 v230, vcc, 0x10000, v152
	s_nop 1
	v_addc_co_u32_e32 v231, vcc, 0, v153, vcc
	global_load_dwordx2 v[180:181], v[230:231], off
	global_load_dwordx2 v[182:183], v[230:231], off offset:32
	global_load_dwordx2 v[184:185], v[230:231], off offset:256
	global_load_dwordx2 v[188:189], v[230:231], off offset:288
	v_add_co_u32_e32 v230, vcc, 0x18000, v152
	s_nop 1
	v_addc_co_u32_e32 v231, vcc, 0, v153, vcc
	global_load_dwordx2 v[190:191], v[230:231], off
	global_load_dwordx2 v[192:193], v[230:231], off offset:32
	global_load_dwordx2 v[194:195], v[230:231], off offset:256
	global_load_dwordx2 v[196:197], v[230:231], off offset:288
	v_add_co_u32_e32 v230, vcc, 0x40000, v152
	s_nop 1
	v_addc_co_u32_e32 v231, vcc, 0, v153, vcc
	global_load_dwordx2 v[198:199], v[230:231], off
	global_load_dwordx2 v[200:201], v[230:231], off offset:32
	global_load_dwordx2 v[202:203], v[230:231], off offset:256
	global_load_dwordx2 v[204:205], v[230:231], off offset:288
	v_add_co_u32_e32 v230, vcc, 0x48000, v152
	s_nop 1
	v_addc_co_u32_e32 v231, vcc, 0, v153, vcc
	global_load_dwordx2 v[206:207], v[230:231], off
	global_load_dwordx2 v[208:209], v[230:231], off offset:32
	global_load_dwordx2 v[210:211], v[230:231], off offset:256
	global_load_dwordx2 v[212:213], v[230:231], off offset:288
	v_add_co_u32_e32 v230, vcc, 0x50000, v152
	s_nop 1
	v_addc_co_u32_e32 v231, vcc, 0, v153, vcc
	global_load_dwordx2 v[214:215], v[230:231], off
	global_load_dwordx2 v[216:217], v[230:231], off offset:32
	global_load_dwordx2 v[218:219], v[230:231], off offset:256
	global_load_dwordx2 v[220:221], v[230:231], off offset:288
	v_add_co_u32_e32 v230, vcc, 0x58000, v152
	s_nop 1
	v_addc_co_u32_e32 v231, vcc, 0, v153, vcc
	global_load_dwordx2 v[222:223], v[230:231], off
	global_load_dwordx2 v[224:225], v[230:231], off offset:32
	global_load_dwordx2 v[226:227], v[230:231], off offset:256
	global_load_dwordx2 v[228:229], v[230:231], off offset:288
	s_waitcnt vmcnt(0)
	s_lshl_b32 s26, s10, 2
	s_ashr_i32 s27, s26, 31
	v_mov_b64_e32 v[154:155], v[164:165]
	v_lshlrev_b32_e32 v156, 16, v154
	v_and_b32_e32 v157, 0xffff0000, v154
	v_lshlrev_b32_e32 v154, 16, v155
	v_and_b32_e32 v155, 0xffff0000, v155
	v_pk_add_f32 v[126:127], v[126:127], v[154:155]
	v_pk_add_f32 v[124:125], v[124:125], v[156:157]
	s_nop 0
	v_cvt_pk_bf16_f32 v154, v124, v125
	v_cvt_pk_bf16_f32 v155, v126, v127
	v_mul_f32_e32 v125, v125, v125
	global_store_dwordx2 v[152:153], v[154:155], off
	v_mul_f32_e32 v127, v127, v127
	v_fmac_f32_e32 v125, v124, v124
	v_fmac_f32_e32 v127, v126, v126
	v_add_f32_e32 v124, v125, v127
	v_mov_b64_e32 v[156:157], v[166:167]
	v_lshlrev_b32_e32 v154, 16, v156
	v_and_b32_e32 v155, 0xffff0000, v156
	v_lshlrev_b32_e32 v156, 16, v157
	v_and_b32_e32 v157, 0xffff0000, v157
	v_pk_add_f32 v[122:123], v[122:123], v[156:157]
	v_pk_add_f32 v[120:121], v[120:121], v[154:155]
	s_nop 0
	v_cvt_pk_bf16_f32 v154, v120, v121
	v_cvt_pk_bf16_f32 v155, v122, v123
	v_mul_f32_e32 v121, v121, v121
	global_store_dwordx2 v[152:153], v[154:155], off offset:32
	v_mul_f32_e32 v123, v123, v123
	v_fmac_f32_e32 v121, v120, v120
	v_fmac_f32_e32 v123, v122, v122
	v_add_f32_e32 v120, v121, v123
	v_add_f32_e32 v120, v124, v120
	v_mov_b64_e32 v[156:157], v[168:169]
	v_lshlrev_b32_e32 v154, 16, v156
	v_and_b32_e32 v155, 0xffff0000, v156
	v_lshlrev_b32_e32 v156, 16, v157
	v_and_b32_e32 v157, 0xffff0000, v157
	v_pk_add_f32 v[118:119], v[118:119], v[156:157]
	v_pk_add_f32 v[154:155], v[116:117], v[154:155]
	v_and_b32_e32 v117, 64, v150
	v_cvt_pk_bf16_f32 v156, v154, v155
	v_cvt_pk_bf16_f32 v157, v118, v119
	v_mul_f32_e32 v121, v155, v155
	v_mul_f32_e32 v119, v119, v119
	v_fmac_f32_e32 v121, v154, v154
	v_fmac_f32_e32 v119, v118, v118
	v_add_f32_e32 v118, v121, v119
	v_add_f32_e32 v122, v120, v118
	v_xor_b32_e32 v116, 16, v150
	v_add_u32_e32 v117, 64, v117
	v_cmp_lt_i32_e32 vcc, v116, v117
	global_store_dwordx2 v[152:153], v[156:157], off offset:256
	v_mov_b64_e32 v[158:159], v[170:171]
	v_lshlrev_b32_e32 v118, 16, v158
	v_and_b32_e32 v119, 0xffff0000, v158
	v_lshlrev_b32_e32 v120, 16, v159
	v_and_b32_e32 v121, 0xffff0000, v159
	v_pk_add_f32 v[120:121], v[114:115], v[120:121]
	v_pk_add_f32 v[118:119], v[112:113], v[118:119]
	v_mul_f32_e32 v113, v121, v121
	v_mul_f32_e32 v112, v119, v119
	v_fmac_f32_e32 v112, v118, v118
	v_fmac_f32_e32 v113, v120, v120
	v_cndmask_b32_e32 v116, v150, v116, vcc
	v_add_f32_e32 v112, v112, v113
	v_lshlrev_b32_e32 v116, 2, v116
	v_add_f32_e32 v112, v122, v112
	ds_bpermute_b32 v113, v116, v112
	v_xor_b32_e32 v114, 32, v150
	v_cmp_lt_i32_e32 vcc, v114, v117
	v_cvt_pk_bf16_f32 v118, v118, v119
	v_cvt_pk_bf16_f32 v119, v120, v121
	s_waitcnt lgkmcnt(0)
	v_add_f32_e32 v112, v112, v113
	global_store_dwordx2 v[152:153], v[118:119], off offset:288
	v_cndmask_b32_e32 v114, v150, v114, vcc
	v_lshlrev_b32_e32 v114, 2, v114
	ds_bpermute_b32 v113, v114, v112
	s_and_saveexec_b64 s[28:29], s[4:5]
	s_cbranch_execz .LBB0_934
	s_waitcnt lgkmcnt(0)
	v_add_f32_e32 v115, v112, v113
	v_lshlrev_b64 v[112:113], 6, v[144:145]
	v_lshl_add_u64 v[112:113], s[60:61], 0, v[112:113]
	v_lshl_add_u64 v[112:113], s[26:27], 2, v[112:113]
	s_lshl_b32 s10, s44, 2
	v_lshl_add_u64 v[112:113], v[112:113], 0, s[10:11]
	global_store_dword v[112:113], v115, off
.LBB0_934:
	s_or_b64 exec, exec, s[28:29]
	v_or_b32_e32 v112, 16, v144
	s_waitcnt lgkmcnt(0)
	v_ashrrev_i32_e32 v113, 31, v112
	v_lshlrev_b64 v[118:119], 11, v[112:113]
	v_lshl_add_u64 v[118:119], s[62:63], 0, v[118:119]
	v_lshl_add_u64 v[118:119], v[142:143], 1, v[118:119]
	v_mov_b64_e32 v[120:121], v[172:173]
	v_lshlrev_b32_e32 v122, 16, v120
	v_and_b32_e32 v123, 0xffff0000, v120
	v_lshlrev_b32_e32 v120, 16, v121
	v_and_b32_e32 v121, 0xffff0000, v121
	v_pk_add_f32 v[110:111], v[110:111], v[120:121]
	v_pk_add_f32 v[108:109], v[108:109], v[122:123]
	s_nop 0
	v_cvt_pk_bf16_f32 v120, v108, v109
	v_cvt_pk_bf16_f32 v121, v110, v111
	v_mul_f32_e32 v109, v109, v109
	global_store_dwordx2 v[118:119], v[120:121], off
	v_mul_f32_e32 v111, v111, v111
	v_fmac_f32_e32 v109, v108, v108
	v_fmac_f32_e32 v111, v110, v110
	v_add_f32_e32 v108, v109, v111
	v_mov_b64_e32 v[122:123], v[174:175]
	v_lshlrev_b32_e32 v120, 16, v122
	v_and_b32_e32 v121, 0xffff0000, v122
	v_lshlrev_b32_e32 v122, 16, v123
	v_and_b32_e32 v123, 0xffff0000, v123
	v_pk_add_f32 v[106:107], v[106:107], v[122:123]
	v_pk_add_f32 v[104:105], v[104:105], v[120:121]
	s_nop 0
	v_cvt_pk_bf16_f32 v120, v104, v105
	v_cvt_pk_bf16_f32 v121, v106, v107
	v_mul_f32_e32 v105, v105, v105
	global_store_dwordx2 v[118:119], v[120:121], off offset:32
	v_mul_f32_e32 v107, v107, v107
	v_fmac_f32_e32 v105, v104, v104
	v_fmac_f32_e32 v107, v106, v106
	v_add_f32_e32 v104, v105, v107
	v_add_f32_e32 v104, v108, v104
	v_mov_b64_e32 v[122:123], v[176:177]
	v_lshlrev_b32_e32 v120, 16, v122
	v_and_b32_e32 v121, 0xffff0000, v122
	v_lshlrev_b32_e32 v122, 16, v123
	v_and_b32_e32 v123, 0xffff0000, v123
	v_pk_add_f32 v[102:103], v[102:103], v[122:123]
	v_pk_add_f32 v[100:101], v[100:101], v[120:121]
	s_nop 0
	v_cvt_pk_bf16_f32 v120, v100, v101
	v_cvt_pk_bf16_f32 v121, v102, v103
	v_mul_f32_e32 v101, v101, v101
	v_mul_f32_e32 v103, v103, v103
	v_fmac_f32_e32 v101, v100, v100
	v_fmac_f32_e32 v103, v102, v102
	v_add_f32_e32 v100, v101, v103
	v_add_f32_e32 v104, v104, v100
	global_store_dwordx2 v[118:119], v[120:121], off offset:256
	v_mov_b64_e32 v[122:123], v[178:179]
	v_lshlrev_b32_e32 v100, 16, v122
	v_and_b32_e32 v101, 0xffff0000, v122
	v_lshlrev_b32_e32 v102, 16, v123
	v_and_b32_e32 v103, 0xffff0000, v123
	v_pk_add_f32 v[98:99], v[98:99], v[102:103]
	v_pk_add_f32 v[100:101], v[96:97], v[100:101]
	v_mul_f32_e32 v97, v99, v99
	v_mul_f32_e32 v96, v101, v101
	v_fmac_f32_e32 v96, v100, v100
	v_fmac_f32_e32 v97, v98, v98
	v_add_f32_e32 v96, v96, v97
	v_add_f32_e32 v96, v104, v96
	ds_bpermute_b32 v97, v116, v96
	v_cvt_pk_bf16_f32 v100, v100, v101
	v_cvt_pk_bf16_f32 v101, v98, v99
	global_store_dwordx2 v[118:119], v[100:101], off offset:288
	s_waitcnt lgkmcnt(0)
	v_add_f32_e32 v96, v96, v97
	ds_bpermute_b32 v97, v114, v96
	s_and_saveexec_b64 s[28:29], s[4:5]
	s_cbranch_execz .LBB0_936
	s_waitcnt lgkmcnt(0)
	v_add_f32_e32 v98, v96, v97
	v_lshlrev_b64 v[96:97], 6, v[112:113]
	v_lshl_add_u64 v[96:97], s[60:61], 0, v[96:97]
	v_lshl_add_u64 v[96:97], s[26:27], 2, v[96:97]
	s_lshl_b32 s10, s44, 2
	v_lshl_add_u64 v[96:97], v[96:97], 0, s[10:11]
	global_store_dword v[96:97], v98, off
.LBB0_936:
	s_or_b64 exec, exec, s[28:29]
	v_or_b32_e32 v96, 32, v144
	s_waitcnt lgkmcnt(0)
	v_ashrrev_i32_e32 v97, 31, v96
	v_lshlrev_b64 v[98:99], 11, v[96:97]
	v_lshl_add_u64 v[98:99], s[62:63], 0, v[98:99]
	v_lshl_add_u64 v[98:99], v[142:143], 1, v[98:99]
	v_mov_b64_e32 v[100:101], v[180:181]
	v_lshlrev_b32_e32 v102, 16, v100
	v_and_b32_e32 v103, 0xffff0000, v100
	v_lshlrev_b32_e32 v100, 16, v101
	v_and_b32_e32 v101, 0xffff0000, v101
	v_pk_add_f32 v[94:95], v[94:95], v[100:101]
	v_pk_add_f32 v[92:93], v[92:93], v[102:103]
	s_nop 0
	v_cvt_pk_bf16_f32 v100, v92, v93
	v_cvt_pk_bf16_f32 v101, v94, v95
	v_mul_f32_e32 v93, v93, v93
	global_store_dwordx2 v[98:99], v[100:101], off
	v_mul_f32_e32 v95, v95, v95
	v_fmac_f32_e32 v93, v92, v92
	v_fmac_f32_e32 v95, v94, v94
	v_add_f32_e32 v92, v93, v95
	v_mov_b64_e32 v[102:103], v[182:183]
	v_lshlrev_b32_e32 v100, 16, v102
	v_and_b32_e32 v101, 0xffff0000, v102
	v_lshlrev_b32_e32 v102, 16, v103
	v_and_b32_e32 v103, 0xffff0000, v103
	v_pk_add_f32 v[90:91], v[90:91], v[102:103]
	v_pk_add_f32 v[88:89], v[88:89], v[100:101]
	s_nop 0
	v_cvt_pk_bf16_f32 v100, v88, v89
	v_cvt_pk_bf16_f32 v101, v90, v91
	v_mul_f32_e32 v89, v89, v89
	global_store_dwordx2 v[98:99], v[100:101], off offset:32
	v_mul_f32_e32 v91, v91, v91
	v_fmac_f32_e32 v89, v88, v88
	v_fmac_f32_e32 v91, v90, v90
	v_add_f32_e32 v88, v89, v91
	v_add_f32_e32 v88, v92, v88
	v_mov_b64_e32 v[102:103], v[184:185]
	v_lshlrev_b32_e32 v100, 16, v102
	v_and_b32_e32 v101, 0xffff0000, v102
	v_lshlrev_b32_e32 v102, 16, v103
	v_and_b32_e32 v103, 0xffff0000, v103
	v_pk_add_f32 v[86:87], v[86:87], v[102:103]
	v_pk_add_f32 v[84:85], v[84:85], v[100:101]
	s_nop 0
	v_cvt_pk_bf16_f32 v100, v84, v85
	v_cvt_pk_bf16_f32 v101, v86, v87
	v_mul_f32_e32 v85, v85, v85
	v_mul_f32_e32 v87, v87, v87
	v_fmac_f32_e32 v85, v84, v84
	v_fmac_f32_e32 v87, v86, v86
	v_add_f32_e32 v84, v85, v87
	v_add_f32_e32 v88, v88, v84
	global_store_dwordx2 v[98:99], v[100:101], off offset:256
	v_mov_b64_e32 v[102:103], v[188:189]
	v_lshlrev_b32_e32 v84, 16, v102
	v_and_b32_e32 v85, 0xffff0000, v102
	v_lshlrev_b32_e32 v86, 16, v103
	v_and_b32_e32 v87, 0xffff0000, v103
	v_pk_add_f32 v[82:83], v[82:83], v[86:87]
	v_pk_add_f32 v[84:85], v[80:81], v[84:85]
	v_mul_f32_e32 v81, v83, v83
	v_mul_f32_e32 v80, v85, v85
	v_fmac_f32_e32 v80, v84, v84
	v_fmac_f32_e32 v81, v82, v82
	v_add_f32_e32 v80, v80, v81
	v_add_f32_e32 v80, v88, v80
	ds_bpermute_b32 v81, v116, v80
	v_cvt_pk_bf16_f32 v84, v84, v85
	v_cvt_pk_bf16_f32 v85, v82, v83
	global_store_dwordx2 v[98:99], v[84:85], off offset:288
	s_waitcnt lgkmcnt(0)
	v_add_f32_e32 v80, v80, v81
	ds_bpermute_b32 v81, v114, v80
	s_and_saveexec_b64 s[28:29], s[4:5]
	s_cbranch_execz .LBB0_938
	s_waitcnt lgkmcnt(0)
	v_add_f32_e32 v82, v80, v81
	v_lshlrev_b64 v[80:81], 6, v[96:97]
	v_lshl_add_u64 v[80:81], s[60:61], 0, v[80:81]
	v_lshl_add_u64 v[80:81], s[26:27], 2, v[80:81]
	s_lshl_b32 s10, s44, 2
	v_lshl_add_u64 v[80:81], v[80:81], 0, s[10:11]
	global_store_dword v[80:81], v82, off
.LBB0_938:
	s_or_b64 exec, exec, s[28:29]
	v_or_b32_e32 v80, 48, v144
	s_waitcnt lgkmcnt(0)
	v_ashrrev_i32_e32 v81, 31, v80
	v_lshlrev_b64 v[82:83], 11, v[80:81]
	v_lshl_add_u64 v[82:83], s[62:63], 0, v[82:83]
	v_lshl_add_u64 v[82:83], v[142:143], 1, v[82:83]
	v_mov_b64_e32 v[84:85], v[190:191]
	v_lshlrev_b32_e32 v86, 16, v84
	v_and_b32_e32 v87, 0xffff0000, v84
	v_lshlrev_b32_e32 v84, 16, v85
	v_and_b32_e32 v85, 0xffff0000, v85
	v_pk_add_f32 v[78:79], v[78:79], v[84:85]
	v_pk_add_f32 v[76:77], v[76:77], v[86:87]
	s_nop 0
	v_cvt_pk_bf16_f32 v84, v76, v77
	v_cvt_pk_bf16_f32 v85, v78, v79
	v_mul_f32_e32 v77, v77, v77
	global_store_dwordx2 v[82:83], v[84:85], off
	v_mul_f32_e32 v79, v79, v79
	v_fmac_f32_e32 v77, v76, v76
	v_fmac_f32_e32 v79, v78, v78
	v_add_f32_e32 v76, v77, v79
	v_mov_b64_e32 v[86:87], v[192:193]
	v_lshlrev_b32_e32 v84, 16, v86
	v_and_b32_e32 v85, 0xffff0000, v86
	v_lshlrev_b32_e32 v86, 16, v87
	v_and_b32_e32 v87, 0xffff0000, v87
	v_pk_add_f32 v[74:75], v[74:75], v[86:87]
	v_pk_add_f32 v[72:73], v[72:73], v[84:85]
	s_nop 0
	v_cvt_pk_bf16_f32 v84, v72, v73
	v_cvt_pk_bf16_f32 v85, v74, v75
	v_mul_f32_e32 v73, v73, v73
	global_store_dwordx2 v[82:83], v[84:85], off offset:32
	v_mul_f32_e32 v75, v75, v75
	v_fmac_f32_e32 v73, v72, v72
	v_fmac_f32_e32 v75, v74, v74
	v_add_f32_e32 v72, v73, v75
	v_add_f32_e32 v72, v76, v72
	v_mov_b64_e32 v[86:87], v[194:195]
	v_lshlrev_b32_e32 v84, 16, v86
	v_and_b32_e32 v85, 0xffff0000, v86
	v_lshlrev_b32_e32 v86, 16, v87
	v_and_b32_e32 v87, 0xffff0000, v87
	v_pk_add_f32 v[70:71], v[70:71], v[86:87]
	v_pk_add_f32 v[68:69], v[68:69], v[84:85]
	s_nop 0
	v_cvt_pk_bf16_f32 v84, v68, v69
	v_cvt_pk_bf16_f32 v85, v70, v71
	v_mul_f32_e32 v69, v69, v69
	v_mul_f32_e32 v71, v71, v71
	v_fmac_f32_e32 v69, v68, v68
	v_fmac_f32_e32 v71, v70, v70
	v_add_f32_e32 v68, v69, v71
	v_add_f32_e32 v72, v72, v68
	global_store_dwordx2 v[82:83], v[84:85], off offset:256
	v_mov_b64_e32 v[86:87], v[196:197]
	v_lshlrev_b32_e32 v68, 16, v86
	v_and_b32_e32 v69, 0xffff0000, v86
	v_lshlrev_b32_e32 v70, 16, v87
	v_and_b32_e32 v71, 0xffff0000, v87
	v_pk_add_f32 v[66:67], v[66:67], v[70:71]
	v_pk_add_f32 v[68:69], v[64:65], v[68:69]
	v_mul_f32_e32 v65, v67, v67
	v_mul_f32_e32 v64, v69, v69
	v_fmac_f32_e32 v64, v68, v68
	v_fmac_f32_e32 v65, v66, v66
	v_add_f32_e32 v64, v64, v65
	v_add_f32_e32 v64, v72, v64
	ds_bpermute_b32 v65, v116, v64
	v_cvt_pk_bf16_f32 v68, v68, v69
	v_cvt_pk_bf16_f32 v69, v66, v67
	global_store_dwordx2 v[82:83], v[68:69], off offset:288
	s_waitcnt lgkmcnt(0)
	v_add_f32_e32 v64, v64, v65
	ds_bpermute_b32 v65, v114, v64
	s_and_saveexec_b64 s[28:29], s[4:5]
	s_cbranch_execz .LBB0_940
	s_waitcnt lgkmcnt(0)
	v_add_f32_e32 v66, v64, v65
	v_lshlrev_b64 v[64:65], 6, v[80:81]
	v_lshl_add_u64 v[64:65], s[60:61], 0, v[64:65]
	v_lshl_add_u64 v[64:65], s[26:27], 2, v[64:65]
	s_lshl_b32 s10, s44, 2
	v_lshl_add_u64 v[64:65], v[64:65], 0, s[10:11]
	global_store_dword v[64:65], v66, off
.LBB0_940:
	s_or_b64 exec, exec, s[28:29]
	v_add_u32_e32 v64, 0x80, v144
	s_waitcnt lgkmcnt(0)
	v_ashrrev_i32_e32 v65, 31, v64
	v_lshlrev_b64 v[66:67], 11, v[64:65]
	v_lshl_add_u64 v[66:67], s[62:63], 0, v[66:67]
	v_lshl_add_u64 v[66:67], v[142:143], 1, v[66:67]
	v_mov_b64_e32 v[68:69], v[198:199]
	v_lshlrev_b32_e32 v70, 16, v68
	v_and_b32_e32 v71, 0xffff0000, v68
	v_lshlrev_b32_e32 v68, 16, v69
	v_and_b32_e32 v69, 0xffff0000, v69
	v_pk_add_f32 v[62:63], v[62:63], v[68:69]
	v_pk_add_f32 v[60:61], v[60:61], v[70:71]
	s_nop 0
	v_cvt_pk_bf16_f32 v68, v60, v61
	v_cvt_pk_bf16_f32 v69, v62, v63
	v_mul_f32_e32 v61, v61, v61
	global_store_dwordx2 v[66:67], v[68:69], off
	v_mul_f32_e32 v63, v63, v63
	v_fmac_f32_e32 v61, v60, v60
	v_fmac_f32_e32 v63, v62, v62
	v_add_f32_e32 v60, v61, v63
	v_mov_b64_e32 v[70:71], v[200:201]
	v_lshlrev_b32_e32 v68, 16, v70
	v_and_b32_e32 v69, 0xffff0000, v70
	v_lshlrev_b32_e32 v70, 16, v71
	v_and_b32_e32 v71, 0xffff0000, v71
	v_pk_add_f32 v[58:59], v[58:59], v[70:71]
	v_pk_add_f32 v[56:57], v[56:57], v[68:69]
	s_nop 0
	v_cvt_pk_bf16_f32 v68, v56, v57
	v_cvt_pk_bf16_f32 v69, v58, v59
	v_mul_f32_e32 v57, v57, v57
	global_store_dwordx2 v[66:67], v[68:69], off offset:32
	v_mul_f32_e32 v59, v59, v59
	v_fmac_f32_e32 v57, v56, v56
	v_fmac_f32_e32 v59, v58, v58
	v_add_f32_e32 v56, v57, v59
	v_add_f32_e32 v56, v60, v56
	v_mov_b64_e32 v[70:71], v[202:203]
	v_lshlrev_b32_e32 v68, 16, v70
	v_and_b32_e32 v69, 0xffff0000, v70
	v_lshlrev_b32_e32 v70, 16, v71
	v_and_b32_e32 v71, 0xffff0000, v71
	v_pk_add_f32 v[54:55], v[54:55], v[70:71]
	v_pk_add_f32 v[52:53], v[52:53], v[68:69]
	s_nop 0
	v_cvt_pk_bf16_f32 v68, v52, v53
	v_cvt_pk_bf16_f32 v69, v54, v55
	v_mul_f32_e32 v53, v53, v53
	v_mul_f32_e32 v55, v55, v55
	v_fmac_f32_e32 v53, v52, v52
	v_fmac_f32_e32 v55, v54, v54
	v_add_f32_e32 v52, v53, v55
	v_add_f32_e32 v56, v56, v52
	global_store_dwordx2 v[66:67], v[68:69], off offset:256
	v_mov_b64_e32 v[70:71], v[204:205]
	v_lshlrev_b32_e32 v52, 16, v70
	v_and_b32_e32 v53, 0xffff0000, v70
	v_lshlrev_b32_e32 v54, 16, v71
	v_and_b32_e32 v55, 0xffff0000, v71
	v_pk_add_f32 v[50:51], v[50:51], v[54:55]
	v_pk_add_f32 v[52:53], v[48:49], v[52:53]
	v_mul_f32_e32 v49, v51, v51
	v_mul_f32_e32 v48, v53, v53
	v_fmac_f32_e32 v48, v52, v52
	v_fmac_f32_e32 v49, v50, v50
	v_add_f32_e32 v48, v48, v49
	v_add_f32_e32 v48, v56, v48
	ds_bpermute_b32 v49, v116, v48
	v_cvt_pk_bf16_f32 v52, v52, v53
	v_cvt_pk_bf16_f32 v53, v50, v51
	global_store_dwordx2 v[66:67], v[52:53], off offset:288
	s_waitcnt lgkmcnt(0)
	v_add_f32_e32 v48, v48, v49
	ds_bpermute_b32 v49, v114, v48
	s_and_saveexec_b64 s[28:29], s[4:5]
	s_cbranch_execz .LBB0_942
	s_waitcnt lgkmcnt(0)
	v_add_f32_e32 v50, v48, v49
	v_lshlrev_b64 v[48:49], 6, v[64:65]
	v_lshl_add_u64 v[48:49], s[60:61], 0, v[48:49]
	v_lshl_add_u64 v[48:49], s[26:27], 2, v[48:49]
	s_lshl_b32 s10, s44, 2
	v_lshl_add_u64 v[48:49], v[48:49], 0, s[10:11]
	global_store_dword v[48:49], v50, off
.LBB0_942:
	s_or_b64 exec, exec, s[28:29]
	v_add_u32_e32 v48, 0x90, v144
	s_waitcnt lgkmcnt(0)
	v_ashrrev_i32_e32 v49, 31, v48
	v_lshlrev_b64 v[50:51], 11, v[48:49]
	v_lshl_add_u64 v[50:51], s[62:63], 0, v[50:51]
	v_lshl_add_u64 v[50:51], v[142:143], 1, v[50:51]
	v_mov_b64_e32 v[52:53], v[206:207]
	v_lshlrev_b32_e32 v54, 16, v52
	v_and_b32_e32 v55, 0xffff0000, v52
	v_lshlrev_b32_e32 v52, 16, v53
	v_and_b32_e32 v53, 0xffff0000, v53
	v_pk_add_f32 v[46:47], v[46:47], v[52:53]
	v_pk_add_f32 v[44:45], v[44:45], v[54:55]
	s_nop 0
	v_cvt_pk_bf16_f32 v52, v44, v45
	v_cvt_pk_bf16_f32 v53, v46, v47
	v_mul_f32_e32 v45, v45, v45
	global_store_dwordx2 v[50:51], v[52:53], off
	v_mul_f32_e32 v47, v47, v47
	v_fmac_f32_e32 v45, v44, v44
	v_fmac_f32_e32 v47, v46, v46
	v_add_f32_e32 v44, v45, v47
	v_mov_b64_e32 v[54:55], v[208:209]
	v_lshlrev_b32_e32 v52, 16, v54
	v_and_b32_e32 v53, 0xffff0000, v54
	v_lshlrev_b32_e32 v54, 16, v55
	v_and_b32_e32 v55, 0xffff0000, v55
	v_pk_add_f32 v[42:43], v[42:43], v[54:55]
	v_pk_add_f32 v[40:41], v[40:41], v[52:53]
	s_nop 0
	v_cvt_pk_bf16_f32 v52, v40, v41
	v_cvt_pk_bf16_f32 v53, v42, v43
	v_mul_f32_e32 v41, v41, v41
	global_store_dwordx2 v[50:51], v[52:53], off offset:32
	v_mul_f32_e32 v43, v43, v43
	v_fmac_f32_e32 v41, v40, v40
	v_fmac_f32_e32 v43, v42, v42
	v_add_f32_e32 v40, v41, v43
	v_add_f32_e32 v40, v44, v40
	v_mov_b64_e32 v[54:55], v[210:211]
	v_lshlrev_b32_e32 v52, 16, v54
	v_and_b32_e32 v53, 0xffff0000, v54
	v_lshlrev_b32_e32 v54, 16, v55
	v_and_b32_e32 v55, 0xffff0000, v55
	v_pk_add_f32 v[38:39], v[38:39], v[54:55]
	v_pk_add_f32 v[36:37], v[36:37], v[52:53]
	s_nop 0
	v_cvt_pk_bf16_f32 v52, v36, v37
	v_cvt_pk_bf16_f32 v53, v38, v39
	v_mul_f32_e32 v37, v37, v37
	v_mul_f32_e32 v39, v39, v39
	v_fmac_f32_e32 v37, v36, v36
	v_fmac_f32_e32 v39, v38, v38
	v_add_f32_e32 v36, v37, v39
	v_add_f32_e32 v40, v40, v36
	global_store_dwordx2 v[50:51], v[52:53], off offset:256
	v_mov_b64_e32 v[54:55], v[212:213]
	v_lshlrev_b32_e32 v36, 16, v54
	v_and_b32_e32 v37, 0xffff0000, v54
	v_lshlrev_b32_e32 v38, 16, v55
	v_and_b32_e32 v39, 0xffff0000, v55
	v_pk_add_f32 v[34:35], v[34:35], v[38:39]
	v_pk_add_f32 v[36:37], v[32:33], v[36:37]
	v_mul_f32_e32 v33, v35, v35
	v_mul_f32_e32 v32, v37, v37
	v_fmac_f32_e32 v32, v36, v36
	v_fmac_f32_e32 v33, v34, v34
	v_add_f32_e32 v32, v32, v33
	v_add_f32_e32 v32, v40, v32
	ds_bpermute_b32 v33, v116, v32
	v_cvt_pk_bf16_f32 v36, v36, v37
	v_cvt_pk_bf16_f32 v37, v34, v35
	global_store_dwordx2 v[50:51], v[36:37], off offset:288
	s_waitcnt lgkmcnt(0)
	v_add_f32_e32 v32, v32, v33
	ds_bpermute_b32 v33, v114, v32
	s_and_saveexec_b64 s[28:29], s[4:5]
	s_cbranch_execz .LBB0_944
	s_waitcnt lgkmcnt(0)
	v_add_f32_e32 v34, v32, v33
	v_lshlrev_b64 v[32:33], 6, v[48:49]
	v_lshl_add_u64 v[32:33], s[60:61], 0, v[32:33]
	v_lshl_add_u64 v[32:33], s[26:27], 2, v[32:33]
	s_lshl_b32 s10, s44, 2
	v_lshl_add_u64 v[32:33], v[32:33], 0, s[10:11]
	global_store_dword v[32:33], v34, off
.LBB0_944:
	s_or_b64 exec, exec, s[28:29]
	v_add_u32_e32 v32, 0xa0, v144
	s_waitcnt lgkmcnt(0)
	v_ashrrev_i32_e32 v33, 31, v32
	v_lshlrev_b64 v[34:35], 11, v[32:33]
	v_lshl_add_u64 v[34:35], s[62:63], 0, v[34:35]
	v_lshl_add_u64 v[34:35], v[142:143], 1, v[34:35]
	v_mov_b64_e32 v[36:37], v[214:215]
	v_lshlrev_b32_e32 v38, 16, v36
	v_and_b32_e32 v39, 0xffff0000, v36
	v_lshlrev_b32_e32 v36, 16, v37
	v_and_b32_e32 v37, 0xffff0000, v37
	v_pk_add_f32 v[30:31], v[30:31], v[36:37]
	v_pk_add_f32 v[28:29], v[28:29], v[38:39]
	s_nop 0
	v_cvt_pk_bf16_f32 v36, v28, v29
	v_cvt_pk_bf16_f32 v37, v30, v31
	v_mul_f32_e32 v29, v29, v29
	global_store_dwordx2 v[34:35], v[36:37], off
	v_mul_f32_e32 v31, v31, v31
	v_fmac_f32_e32 v29, v28, v28
	v_fmac_f32_e32 v31, v30, v30
	v_add_f32_e32 v28, v29, v31
	v_mov_b64_e32 v[38:39], v[216:217]
	v_lshlrev_b32_e32 v36, 16, v38
	v_and_b32_e32 v37, 0xffff0000, v38
	v_lshlrev_b32_e32 v38, 16, v39
	v_and_b32_e32 v39, 0xffff0000, v39
	v_pk_add_f32 v[26:27], v[26:27], v[38:39]
	v_pk_add_f32 v[24:25], v[24:25], v[36:37]
	s_nop 0
	v_cvt_pk_bf16_f32 v36, v24, v25
	v_cvt_pk_bf16_f32 v37, v26, v27
	v_mul_f32_e32 v25, v25, v25
	global_store_dwordx2 v[34:35], v[36:37], off offset:32
	v_mul_f32_e32 v27, v27, v27
	v_fmac_f32_e32 v25, v24, v24
	v_fmac_f32_e32 v27, v26, v26
	v_add_f32_e32 v24, v25, v27
	v_add_f32_e32 v24, v28, v24
	v_mov_b64_e32 v[38:39], v[218:219]
	v_lshlrev_b32_e32 v36, 16, v38
	v_and_b32_e32 v37, 0xffff0000, v38
	v_lshlrev_b32_e32 v38, 16, v39
	v_and_b32_e32 v39, 0xffff0000, v39
	v_pk_add_f32 v[22:23], v[22:23], v[38:39]
	v_pk_add_f32 v[20:21], v[20:21], v[36:37]
	s_nop 0
	v_cvt_pk_bf16_f32 v36, v20, v21
	v_cvt_pk_bf16_f32 v37, v22, v23
	v_mul_f32_e32 v21, v21, v21
	v_mul_f32_e32 v23, v23, v23
	v_fmac_f32_e32 v21, v20, v20
	v_fmac_f32_e32 v23, v22, v22
	v_add_f32_e32 v20, v21, v23
	v_add_f32_e32 v24, v24, v20
	global_store_dwordx2 v[34:35], v[36:37], off offset:256
	v_mov_b64_e32 v[38:39], v[220:221]
	v_lshlrev_b32_e32 v20, 16, v38
	v_and_b32_e32 v21, 0xffff0000, v38
	v_lshlrev_b32_e32 v22, 16, v39
	v_and_b32_e32 v23, 0xffff0000, v39
	v_pk_add_f32 v[18:19], v[18:19], v[22:23]
	v_pk_add_f32 v[20:21], v[16:17], v[20:21]
	v_mul_f32_e32 v17, v19, v19
	v_mul_f32_e32 v16, v21, v21
	v_fmac_f32_e32 v16, v20, v20
	v_fmac_f32_e32 v17, v18, v18
	v_add_f32_e32 v16, v16, v17
	v_add_f32_e32 v16, v24, v16
	ds_bpermute_b32 v17, v116, v16
	v_cvt_pk_bf16_f32 v20, v20, v21
	v_cvt_pk_bf16_f32 v21, v18, v19
	global_store_dwordx2 v[34:35], v[20:21], off offset:288
	s_waitcnt lgkmcnt(0)
	v_add_f32_e32 v16, v16, v17
	ds_bpermute_b32 v17, v114, v16
	s_and_saveexec_b64 s[28:29], s[4:5]
	s_cbranch_execz .LBB0_946
	s_waitcnt lgkmcnt(0)
	v_add_f32_e32 v18, v16, v17
	v_lshlrev_b64 v[16:17], 6, v[32:33]
	v_lshl_add_u64 v[16:17], s[60:61], 0, v[16:17]
	v_lshl_add_u64 v[16:17], s[26:27], 2, v[16:17]
	s_lshl_b32 s10, s44, 2
	v_lshl_add_u64 v[16:17], v[16:17], 0, s[10:11]
	global_store_dword v[16:17], v18, off
.LBB0_946:
	s_or_b64 exec, exec, s[28:29]
	v_add_u32_e32 v16, 0xb0, v144
	s_waitcnt lgkmcnt(0)
	v_ashrrev_i32_e32 v17, 31, v16
	v_lshlrev_b64 v[18:19], 11, v[16:17]
	v_lshl_add_u64 v[18:19], s[62:63], 0, v[18:19]
	v_lshl_add_u64 v[18:19], v[142:143], 1, v[18:19]
	v_mov_b64_e32 v[20:21], v[222:223]
	v_lshlrev_b32_e32 v22, 16, v20
	v_and_b32_e32 v23, 0xffff0000, v20
	v_lshlrev_b32_e32 v20, 16, v21
	v_and_b32_e32 v21, 0xffff0000, v21
	v_pk_add_f32 v[14:15], v[14:15], v[20:21]
	v_pk_add_f32 v[12:13], v[12:13], v[22:23]
	s_nop 0
	v_cvt_pk_bf16_f32 v20, v12, v13
	v_cvt_pk_bf16_f32 v21, v14, v15
	v_mul_f32_e32 v13, v13, v13
	global_store_dwordx2 v[18:19], v[20:21], off
	v_mul_f32_e32 v15, v15, v15
	v_fmac_f32_e32 v13, v12, v12
	v_fmac_f32_e32 v15, v14, v14
	v_add_f32_e32 v12, v13, v15
	v_mov_b64_e32 v[22:23], v[224:225]
	v_lshlrev_b32_e32 v20, 16, v22
	v_and_b32_e32 v21, 0xffff0000, v22
	v_lshlrev_b32_e32 v22, 16, v23
	v_and_b32_e32 v23, 0xffff0000, v23
	v_pk_add_f32 v[10:11], v[10:11], v[22:23]
	v_pk_add_f32 v[8:9], v[8:9], v[20:21]
	s_nop 0
	v_cvt_pk_bf16_f32 v20, v8, v9
	v_cvt_pk_bf16_f32 v21, v10, v11
	v_mul_f32_e32 v9, v9, v9
	global_store_dwordx2 v[18:19], v[20:21], off offset:32
	v_mul_f32_e32 v11, v11, v11
	v_fmac_f32_e32 v9, v8, v8
	v_fmac_f32_e32 v11, v10, v10
	v_add_f32_e32 v8, v9, v11
	v_add_f32_e32 v8, v12, v8
	v_mov_b64_e32 v[22:23], v[226:227]
	v_lshlrev_b32_e32 v20, 16, v22
	v_and_b32_e32 v21, 0xffff0000, v22
	v_lshlrev_b32_e32 v22, 16, v23
	v_and_b32_e32 v23, 0xffff0000, v23
	v_pk_add_f32 v[6:7], v[6:7], v[22:23]
	v_pk_add_f32 v[4:5], v[4:5], v[20:21]
	s_nop 0
	v_cvt_pk_bf16_f32 v20, v4, v5
	v_cvt_pk_bf16_f32 v21, v6, v7
	v_mul_f32_e32 v5, v5, v5
	v_mul_f32_e32 v7, v7, v7
	v_fmac_f32_e32 v5, v4, v4
	v_fmac_f32_e32 v7, v6, v6
	v_add_f32_e32 v4, v5, v7
	v_add_f32_e32 v8, v8, v4
	global_store_dwordx2 v[18:19], v[20:21], off offset:256
	v_mov_b64_e32 v[22:23], v[228:229]
	v_lshlrev_b32_e32 v4, 16, v22
	v_and_b32_e32 v5, 0xffff0000, v22
	v_lshlrev_b32_e32 v6, 16, v23
	v_and_b32_e32 v7, 0xffff0000, v23
	v_pk_add_f32 v[2:3], v[2:3], v[6:7]
	v_pk_add_f32 v[4:5], v[0:1], v[4:5]
	v_mul_f32_e32 v1, v3, v3
	v_mul_f32_e32 v0, v5, v5
	v_fmac_f32_e32 v0, v4, v4
	v_fmac_f32_e32 v1, v2, v2
	v_add_f32_e32 v0, v0, v1
	v_add_f32_e32 v0, v8, v0
	ds_bpermute_b32 v1, v116, v0
	v_cvt_pk_bf16_f32 v4, v4, v5
	v_cvt_pk_bf16_f32 v5, v2, v3
	global_store_dwordx2 v[18:19], v[4:5], off offset:288
	s_waitcnt lgkmcnt(0)
	v_add_f32_e32 v0, v0, v1
	ds_bpermute_b32 v1, v114, v0
	s_and_saveexec_b64 s[28:29], s[4:5]
	s_cbranch_execz .LBB0_948
	s_waitcnt lgkmcnt(0)
	v_add_f32_e32 v2, v0, v1
	v_lshlrev_b64 v[0:1], 6, v[16:17]
	v_lshl_add_u64 v[0:1], s[60:61], 0, v[0:1]
	v_lshl_add_u64 v[0:1], s[26:27], 2, v[0:1]
	s_lshl_b32 s10, s44, 2
	v_lshl_add_u64 v[0:1], v[0:1], 0, s[10:11]
	global_store_dword v[0:1], v2, off

.LBB0_1606:
	v_lshl_add_u32 v144, s30, 8, v133
	s_lshl_b32 s12, s8, 8
	v_ashrrev_i32_e32 v145, 31, v144
	s_ashr_i32 s13, s12, 31
	v_lshlrev_b64 v[154:155], 11, v[144:145]
	v_mov_b32_e32 v143, s13
	v_or_b32_e32 v142, s12, v132
	v_lshl_add_u64 v[154:155], s[62:63], 0, v[154:155]
	v_lshl_add_u64 v[154:155], v[142:143], 1, v[154:155]
	global_load_dwordx2 v[164:165], v[154:155], off
	global_load_dwordx2 v[166:167], v[154:155], off offset:32
	global_load_dwordx2 v[168:169], v[154:155], off offset:256
	global_load_dwordx2 v[170:171], v[154:155], off offset:288
	v_add_co_u32_e32 v230, vcc, 0x8000, v154
	s_nop 1
	v_addc_co_u32_e32 v231, vcc, 0, v155, vcc
	global_load_dwordx2 v[172:173], v[230:231], off
	global_load_dwordx2 v[174:175], v[230:231], off offset:32
	global_load_dwordx2 v[176:177], v[230:231], off offset:256
	global_load_dwordx2 v[178:179], v[230:231], off offset:288
	v_add_co_u32_e32 v230, vcc, 0x10000, v154
	s_nop 1
	v_addc_co_u32_e32 v231, vcc, 0, v155, vcc
	global_load_dwordx2 v[180:181], v[230:231], off
	global_load_dwordx2 v[182:183], v[230:231], off offset:32
	global_load_dwordx2 v[184:185], v[230:231], off offset:256
	global_load_dwordx2 v[188:189], v[230:231], off offset:288
	v_add_co_u32_e32 v230, vcc, 0x18000, v154
	s_nop 1
	v_addc_co_u32_e32 v231, vcc, 0, v155, vcc
	global_load_dwordx2 v[190:191], v[230:231], off
	global_load_dwordx2 v[192:193], v[230:231], off offset:32
	global_load_dwordx2 v[194:195], v[230:231], off offset:256
	global_load_dwordx2 v[196:197], v[230:231], off offset:288
	v_add_co_u32_e32 v230, vcc, 0x40000, v154
	s_nop 1
	v_addc_co_u32_e32 v231, vcc, 0, v155, vcc
	global_load_dwordx2 v[198:199], v[230:231], off
	global_load_dwordx2 v[200:201], v[230:231], off offset:32
	global_load_dwordx2 v[202:203], v[230:231], off offset:256
	global_load_dwordx2 v[204:205], v[230:231], off offset:288
	v_add_co_u32_e32 v230, vcc, 0x48000, v154
	s_nop 1
	v_addc_co_u32_e32 v231, vcc, 0, v155, vcc
	global_load_dwordx2 v[206:207], v[230:231], off
	global_load_dwordx2 v[208:209], v[230:231], off offset:32
	global_load_dwordx2 v[210:211], v[230:231], off offset:256
	global_load_dwordx2 v[212:213], v[230:231], off offset:288
	v_add_co_u32_e32 v230, vcc, 0x50000, v154
	s_nop 1
	v_addc_co_u32_e32 v231, vcc, 0, v155, vcc
	global_load_dwordx2 v[214:215], v[230:231], off
	global_load_dwordx2 v[216:217], v[230:231], off offset:32
	global_load_dwordx2 v[218:219], v[230:231], off offset:256
	global_load_dwordx2 v[220:221], v[230:231], off offset:288
	v_add_co_u32_e32 v230, vcc, 0x58000, v154
	s_nop 1
	v_addc_co_u32_e32 v231, vcc, 0, v155, vcc
	global_load_dwordx2 v[222:223], v[230:231], off
	global_load_dwordx2 v[224:225], v[230:231], off offset:32
	global_load_dwordx2 v[226:227], v[230:231], off offset:256
	global_load_dwordx2 v[228:229], v[230:231], off offset:288
	s_waitcnt vmcnt(0)
	s_lshl_b32 s30, s8, 2
	s_ashr_i32 s31, s30, 31
	v_mov_b64_e32 v[156:157], v[164:165]
	v_lshlrev_b32_e32 v158, 16, v156
	v_and_b32_e32 v159, 0xffff0000, v156
	v_lshlrev_b32_e32 v156, 16, v157
	v_and_b32_e32 v157, 0xffff0000, v157
	v_pk_add_f32 v[126:127], v[126:127], v[156:157]
	v_pk_add_f32 v[124:125], v[124:125], v[158:159]
	s_nop 0
	v_cvt_pk_bf16_f32 v156, v124, v125
	v_cvt_pk_bf16_f32 v157, v126, v127
	v_mul_f32_e32 v125, v125, v125
	global_store_dwordx2 v[154:155], v[156:157], off
	v_mul_f32_e32 v127, v127, v127
	v_fmac_f32_e32 v125, v124, v124
	v_fmac_f32_e32 v127, v126, v126
	v_add_f32_e32 v124, v125, v127
	v_mov_b64_e32 v[158:159], v[166:167]
	v_lshlrev_b32_e32 v156, 16, v158
	v_and_b32_e32 v157, 0xffff0000, v158
	v_lshlrev_b32_e32 v158, 16, v159
	v_and_b32_e32 v159, 0xffff0000, v159
	v_pk_add_f32 v[122:123], v[122:123], v[158:159]
	v_pk_add_f32 v[120:121], v[120:121], v[156:157]
	s_nop 0
	v_cvt_pk_bf16_f32 v156, v120, v121
	v_cvt_pk_bf16_f32 v157, v122, v123
	v_mul_f32_e32 v121, v121, v121
	global_store_dwordx2 v[154:155], v[156:157], off offset:32
	v_mul_f32_e32 v123, v123, v123
	v_fmac_f32_e32 v121, v120, v120
	v_fmac_f32_e32 v123, v122, v122
	v_add_f32_e32 v120, v121, v123
	v_add_f32_e32 v120, v124, v120
	v_mov_b64_e32 v[158:159], v[168:169]
	v_lshlrev_b32_e32 v156, 16, v158
	v_and_b32_e32 v157, 0xffff0000, v158
	v_lshlrev_b32_e32 v158, 16, v159
	v_and_b32_e32 v159, 0xffff0000, v159
	v_pk_add_f32 v[118:119], v[118:119], v[158:159]
	v_pk_add_f32 v[116:117], v[116:117], v[156:157]
	s_nop 0
	v_cvt_pk_bf16_f32 v156, v116, v117
	v_cvt_pk_bf16_f32 v157, v118, v119
	v_mul_f32_e32 v117, v117, v117
	v_mul_f32_e32 v119, v119, v119
	v_fmac_f32_e32 v117, v116, v116
	v_fmac_f32_e32 v119, v118, v118
	v_add_f32_e32 v116, v117, v119
	v_add_f32_e32 v120, v120, v116
	global_store_dwordx2 v[154:155], v[156:157], off offset:256
	v_mov_b64_e32 v[158:159], v[170:171]
	v_lshlrev_b32_e32 v116, 16, v158
	v_and_b32_e32 v117, 0xffff0000, v158
	v_lshlrev_b32_e32 v118, 16, v159
	v_and_b32_e32 v119, 0xffff0000, v159
	v_pk_add_f32 v[114:115], v[114:115], v[118:119]
	v_pk_add_f32 v[116:117], v[112:113], v[116:117]
	v_mul_f32_e32 v113, v115, v115
	v_mul_f32_e32 v112, v117, v117
	v_fmac_f32_e32 v112, v116, v116
	v_fmac_f32_e32 v113, v114, v114
	v_add_f32_e32 v112, v112, v113
	v_add_f32_e32 v112, v120, v112
	ds_bpermute_b32 v113, v149, v112
	v_cvt_pk_bf16_f32 v116, v116, v117
	v_cvt_pk_bf16_f32 v117, v114, v115
	global_store_dwordx2 v[154:155], v[116:117], off offset:288
	s_waitcnt lgkmcnt(0)
	v_add_f32_e32 v112, v112, v113
	ds_bpermute_b32 v113, v153, v112
	s_and_saveexec_b64 s[36:37], s[4:5]
	s_cbranch_execz .LBB0_1608
	s_waitcnt lgkmcnt(0)
	v_add_f32_e32 v114, v112, v113
	v_lshlrev_b64 v[112:113], 6, v[144:145]
	v_lshl_add_u64 v[112:113], s[60:61], 0, v[112:113]
	v_lshl_add_u64 v[112:113], s[30:31], 2, v[112:113]
	s_lshl_b32 s8, s50, 2
	v_lshl_add_u64 v[112:113], v[112:113], 0, s[8:9]
	global_store_dword v[112:113], v114, off
.LBB0_1608:
	s_or_b64 exec, exec, s[36:37]
	v_or_b32_e32 v112, 16, v144
	s_waitcnt lgkmcnt(0)
	v_ashrrev_i32_e32 v113, 31, v112
	v_lshlrev_b64 v[114:115], 11, v[112:113]
	v_lshl_add_u64 v[114:115], s[62:63], 0, v[114:115]
	v_lshl_add_u64 v[114:115], v[142:143], 1, v[114:115]
	v_mov_b64_e32 v[116:117], v[172:173]
	v_lshlrev_b32_e32 v118, 16, v116
	v_and_b32_e32 v119, 0xffff0000, v116
	v_lshlrev_b32_e32 v116, 16, v117
	v_and_b32_e32 v117, 0xffff0000, v117
	v_pk_add_f32 v[110:111], v[110:111], v[116:117]
	v_pk_add_f32 v[108:109], v[108:109], v[118:119]
	s_nop 0
	v_cvt_pk_bf16_f32 v116, v108, v109
	v_cvt_pk_bf16_f32 v117, v110, v111
	v_mul_f32_e32 v109, v109, v109
	global_store_dwordx2 v[114:115], v[116:117], off
	v_mul_f32_e32 v111, v111, v111
	v_fmac_f32_e32 v109, v108, v108
	v_fmac_f32_e32 v111, v110, v110
	v_add_f32_e32 v108, v109, v111
	v_mov_b64_e32 v[118:119], v[174:175]
	v_lshlrev_b32_e32 v116, 16, v118
	v_and_b32_e32 v117, 0xffff0000, v118
	v_lshlrev_b32_e32 v118, 16, v119
	v_and_b32_e32 v119, 0xffff0000, v119
	v_pk_add_f32 v[106:107], v[106:107], v[118:119]
	v_pk_add_f32 v[104:105], v[104:105], v[116:117]
	s_nop 0
	v_cvt_pk_bf16_f32 v116, v104, v105
	v_cvt_pk_bf16_f32 v117, v106, v107
	v_mul_f32_e32 v105, v105, v105
	global_store_dwordx2 v[114:115], v[116:117], off offset:32
	v_mul_f32_e32 v107, v107, v107
	v_fmac_f32_e32 v105, v104, v104
	v_fmac_f32_e32 v107, v106, v106
	v_add_f32_e32 v104, v105, v107
	v_add_f32_e32 v104, v108, v104
	v_mov_b64_e32 v[118:119], v[176:177]
	v_lshlrev_b32_e32 v116, 16, v118
	v_and_b32_e32 v117, 0xffff0000, v118
	v_lshlrev_b32_e32 v118, 16, v119
	v_and_b32_e32 v119, 0xffff0000, v119
	v_pk_add_f32 v[102:103], v[102:103], v[118:119]
	v_pk_add_f32 v[100:101], v[100:101], v[116:117]
	s_nop 0
	v_cvt_pk_bf16_f32 v116, v100, v101
	v_cvt_pk_bf16_f32 v117, v102, v103
	v_mul_f32_e32 v101, v101, v101
	v_mul_f32_e32 v103, v103, v103
	v_fmac_f32_e32 v101, v100, v100
	v_fmac_f32_e32 v103, v102, v102
	v_add_f32_e32 v100, v101, v103
	v_add_f32_e32 v104, v104, v100
	global_store_dwordx2 v[114:115], v[116:117], off offset:256
	v_mov_b64_e32 v[118:119], v[178:179]
	v_lshlrev_b32_e32 v100, 16, v118
	v_and_b32_e32 v101, 0xffff0000, v118
	v_lshlrev_b32_e32 v102, 16, v119
	v_and_b32_e32 v103, 0xffff0000, v119
	v_pk_add_f32 v[98:99], v[98:99], v[102:103]
	v_pk_add_f32 v[100:101], v[96:97], v[100:101]
	v_mul_f32_e32 v97, v99, v99
	v_mul_f32_e32 v96, v101, v101
	v_fmac_f32_e32 v96, v100, v100
	v_fmac_f32_e32 v97, v98, v98
	v_add_f32_e32 v96, v96, v97
	v_add_f32_e32 v96, v104, v96
	ds_bpermute_b32 v97, v149, v96
	v_cvt_pk_bf16_f32 v100, v100, v101
	v_cvt_pk_bf16_f32 v101, v98, v99
	global_store_dwordx2 v[114:115], v[100:101], off offset:288
	s_waitcnt lgkmcnt(0)
	v_add_f32_e32 v96, v96, v97
	ds_bpermute_b32 v97, v153, v96
	s_and_saveexec_b64 s[36:37], s[4:5]
	s_cbranch_execz .LBB0_1610
	s_waitcnt lgkmcnt(0)
	v_add_f32_e32 v98, v96, v97
	v_lshlrev_b64 v[96:97], 6, v[112:113]
	v_lshl_add_u64 v[96:97], s[60:61], 0, v[96:97]
	v_lshl_add_u64 v[96:97], s[30:31], 2, v[96:97]
	s_lshl_b32 s8, s50, 2
	v_lshl_add_u64 v[96:97], v[96:97], 0, s[8:9]
	global_store_dword v[96:97], v98, off
.LBB0_1610:
	s_or_b64 exec, exec, s[36:37]
	v_or_b32_e32 v96, 32, v144
	s_waitcnt lgkmcnt(0)
	v_ashrrev_i32_e32 v97, 31, v96
	v_lshlrev_b64 v[98:99], 11, v[96:97]
	v_lshl_add_u64 v[98:99], s[62:63], 0, v[98:99]
	v_lshl_add_u64 v[98:99], v[142:143], 1, v[98:99]
	v_mov_b64_e32 v[100:101], v[180:181]
	v_lshlrev_b32_e32 v102, 16, v100
	v_and_b32_e32 v103, 0xffff0000, v100
	v_lshlrev_b32_e32 v100, 16, v101
	v_and_b32_e32 v101, 0xffff0000, v101
	v_pk_add_f32 v[94:95], v[94:95], v[100:101]
	v_pk_add_f32 v[92:93], v[92:93], v[102:103]
	s_nop 0
	v_cvt_pk_bf16_f32 v100, v92, v93
	v_cvt_pk_bf16_f32 v101, v94, v95
	v_mul_f32_e32 v93, v93, v93
	global_store_dwordx2 v[98:99], v[100:101], off
	v_mul_f32_e32 v95, v95, v95
	v_fmac_f32_e32 v93, v92, v92
	v_fmac_f32_e32 v95, v94, v94
	v_add_f32_e32 v92, v93, v95
	v_mov_b64_e32 v[102:103], v[182:183]
	v_lshlrev_b32_e32 v100, 16, v102
	v_and_b32_e32 v101, 0xffff0000, v102
	v_lshlrev_b32_e32 v102, 16, v103
	v_and_b32_e32 v103, 0xffff0000, v103
	v_pk_add_f32 v[90:91], v[90:91], v[102:103]
	v_pk_add_f32 v[88:89], v[88:89], v[100:101]
	s_nop 0
	v_cvt_pk_bf16_f32 v100, v88, v89
	v_cvt_pk_bf16_f32 v101, v90, v91
	v_mul_f32_e32 v89, v89, v89
	global_store_dwordx2 v[98:99], v[100:101], off offset:32
	v_mul_f32_e32 v91, v91, v91
	v_fmac_f32_e32 v89, v88, v88
	v_fmac_f32_e32 v91, v90, v90
	v_add_f32_e32 v88, v89, v91
	v_add_f32_e32 v88, v92, v88
	v_mov_b64_e32 v[102:103], v[184:185]
	v_lshlrev_b32_e32 v100, 16, v102
	v_and_b32_e32 v101, 0xffff0000, v102
	v_lshlrev_b32_e32 v102, 16, v103
	v_and_b32_e32 v103, 0xffff0000, v103
	v_pk_add_f32 v[86:87], v[86:87], v[102:103]
	v_pk_add_f32 v[84:85], v[84:85], v[100:101]
	s_nop 0
	v_cvt_pk_bf16_f32 v100, v84, v85
	v_cvt_pk_bf16_f32 v101, v86, v87
	v_mul_f32_e32 v85, v85, v85
	v_mul_f32_e32 v87, v87, v87
	v_fmac_f32_e32 v85, v84, v84
	v_fmac_f32_e32 v87, v86, v86
	v_add_f32_e32 v84, v85, v87
	v_add_f32_e32 v88, v88, v84
	global_store_dwordx2 v[98:99], v[100:101], off offset:256
	v_mov_b64_e32 v[102:103], v[188:189]
	v_lshlrev_b32_e32 v84, 16, v102
	v_and_b32_e32 v85, 0xffff0000, v102
	v_lshlrev_b32_e32 v86, 16, v103
	v_and_b32_e32 v87, 0xffff0000, v103
	v_pk_add_f32 v[82:83], v[82:83], v[86:87]
	v_pk_add_f32 v[84:85], v[80:81], v[84:85]
	v_mul_f32_e32 v81, v83, v83
	v_mul_f32_e32 v80, v85, v85
	v_fmac_f32_e32 v80, v84, v84
	v_fmac_f32_e32 v81, v82, v82
	v_add_f32_e32 v80, v80, v81
	v_add_f32_e32 v80, v88, v80
	ds_bpermute_b32 v81, v149, v80
	v_cvt_pk_bf16_f32 v84, v84, v85
	v_cvt_pk_bf16_f32 v85, v82, v83
	global_store_dwordx2 v[98:99], v[84:85], off offset:288
	s_waitcnt lgkmcnt(0)
	v_add_f32_e32 v80, v80, v81
	ds_bpermute_b32 v81, v153, v80
	s_and_saveexec_b64 s[36:37], s[4:5]
	s_cbranch_execz .LBB0_1612
	s_waitcnt lgkmcnt(0)
	v_add_f32_e32 v82, v80, v81
	v_lshlrev_b64 v[80:81], 6, v[96:97]
	v_lshl_add_u64 v[80:81], s[60:61], 0, v[80:81]
	v_lshl_add_u64 v[80:81], s[30:31], 2, v[80:81]
	s_lshl_b32 s8, s50, 2
	v_lshl_add_u64 v[80:81], v[80:81], 0, s[8:9]
	global_store_dword v[80:81], v82, off
.LBB0_1612:
	s_or_b64 exec, exec, s[36:37]
	v_or_b32_e32 v80, 48, v144
	s_waitcnt lgkmcnt(0)
	v_ashrrev_i32_e32 v81, 31, v80
	v_lshlrev_b64 v[82:83], 11, v[80:81]
	v_lshl_add_u64 v[82:83], s[62:63], 0, v[82:83]
	v_lshl_add_u64 v[82:83], v[142:143], 1, v[82:83]
	v_mov_b64_e32 v[84:85], v[190:191]
	v_lshlrev_b32_e32 v86, 16, v84
	v_and_b32_e32 v87, 0xffff0000, v84
	v_lshlrev_b32_e32 v84, 16, v85
	v_and_b32_e32 v85, 0xffff0000, v85
	v_pk_add_f32 v[78:79], v[78:79], v[84:85]
	v_pk_add_f32 v[76:77], v[76:77], v[86:87]
	s_nop 0
	v_cvt_pk_bf16_f32 v84, v76, v77
	v_cvt_pk_bf16_f32 v85, v78, v79
	v_mul_f32_e32 v77, v77, v77
	global_store_dwordx2 v[82:83], v[84:85], off
	v_mul_f32_e32 v79, v79, v79
	v_fmac_f32_e32 v77, v76, v76
	v_fmac_f32_e32 v79, v78, v78
	v_add_f32_e32 v76, v77, v79
	v_mov_b64_e32 v[86:87], v[192:193]
	v_lshlrev_b32_e32 v84, 16, v86
	v_and_b32_e32 v85, 0xffff0000, v86
	v_lshlrev_b32_e32 v86, 16, v87
	v_and_b32_e32 v87, 0xffff0000, v87
	v_pk_add_f32 v[74:75], v[74:75], v[86:87]
	v_pk_add_f32 v[72:73], v[72:73], v[84:85]
	s_nop 0
	v_cvt_pk_bf16_f32 v84, v72, v73
	v_cvt_pk_bf16_f32 v85, v74, v75
	v_mul_f32_e32 v73, v73, v73
	global_store_dwordx2 v[82:83], v[84:85], off offset:32
	v_mul_f32_e32 v75, v75, v75
	v_fmac_f32_e32 v73, v72, v72
	v_fmac_f32_e32 v75, v74, v74
	v_add_f32_e32 v72, v73, v75
	v_add_f32_e32 v72, v76, v72
	v_mov_b64_e32 v[86:87], v[194:195]
	v_lshlrev_b32_e32 v84, 16, v86
	v_and_b32_e32 v85, 0xffff0000, v86
	v_lshlrev_b32_e32 v86, 16, v87
	v_and_b32_e32 v87, 0xffff0000, v87
	v_pk_add_f32 v[70:71], v[70:71], v[86:87]
	v_pk_add_f32 v[68:69], v[68:69], v[84:85]
	s_nop 0
	v_cvt_pk_bf16_f32 v84, v68, v69
	v_cvt_pk_bf16_f32 v85, v70, v71
	v_mul_f32_e32 v69, v69, v69
	v_mul_f32_e32 v71, v71, v71
	v_fmac_f32_e32 v69, v68, v68
	v_fmac_f32_e32 v71, v70, v70
	v_add_f32_e32 v68, v69, v71
	v_add_f32_e32 v72, v72, v68
	global_store_dwordx2 v[82:83], v[84:85], off offset:256
	v_mov_b64_e32 v[86:87], v[196:197]
	v_lshlrev_b32_e32 v68, 16, v86
	v_and_b32_e32 v69, 0xffff0000, v86
	v_lshlrev_b32_e32 v70, 16, v87
	v_and_b32_e32 v71, 0xffff0000, v87
	v_pk_add_f32 v[66:67], v[66:67], v[70:71]
	v_pk_add_f32 v[68:69], v[64:65], v[68:69]
	v_mul_f32_e32 v65, v67, v67
	v_mul_f32_e32 v64, v69, v69
	v_fmac_f32_e32 v64, v68, v68
	v_fmac_f32_e32 v65, v66, v66
	v_add_f32_e32 v64, v64, v65
	v_add_f32_e32 v64, v72, v64
	ds_bpermute_b32 v65, v149, v64
	v_cvt_pk_bf16_f32 v68, v68, v69
	v_cvt_pk_bf16_f32 v69, v66, v67
	global_store_dwordx2 v[82:83], v[68:69], off offset:288
	s_waitcnt lgkmcnt(0)
	v_add_f32_e32 v64, v64, v65
	ds_bpermute_b32 v65, v153, v64
	s_and_saveexec_b64 s[36:37], s[4:5]
	s_cbranch_execz .LBB0_1614
	s_waitcnt lgkmcnt(0)
	v_add_f32_e32 v66, v64, v65
	v_lshlrev_b64 v[64:65], 6, v[80:81]
	v_lshl_add_u64 v[64:65], s[60:61], 0, v[64:65]
	v_lshl_add_u64 v[64:65], s[30:31], 2, v[64:65]
	s_lshl_b32 s8, s50, 2
	v_lshl_add_u64 v[64:65], v[64:65], 0, s[8:9]
	global_store_dword v[64:65], v66, off
.LBB0_1614:
	s_or_b64 exec, exec, s[36:37]
	v_add_u32_e32 v64, 0x80, v144
	s_waitcnt lgkmcnt(0)
	v_ashrrev_i32_e32 v65, 31, v64
	v_lshlrev_b64 v[66:67], 11, v[64:65]
	v_lshl_add_u64 v[66:67], s[62:63], 0, v[66:67]
	v_lshl_add_u64 v[66:67], v[142:143], 1, v[66:67]
	v_mov_b64_e32 v[68:69], v[198:199]
	v_lshlrev_b32_e32 v70, 16, v68
	v_and_b32_e32 v71, 0xffff0000, v68
	v_lshlrev_b32_e32 v68, 16, v69
	v_and_b32_e32 v69, 0xffff0000, v69
	v_pk_add_f32 v[62:63], v[62:63], v[68:69]
	v_pk_add_f32 v[60:61], v[60:61], v[70:71]
	s_nop 0
	v_cvt_pk_bf16_f32 v68, v60, v61
	v_cvt_pk_bf16_f32 v69, v62, v63
	v_mul_f32_e32 v61, v61, v61
	global_store_dwordx2 v[66:67], v[68:69], off
	v_mul_f32_e32 v63, v63, v63
	v_fmac_f32_e32 v61, v60, v60
	v_fmac_f32_e32 v63, v62, v62
	v_add_f32_e32 v60, v61, v63
	v_mov_b64_e32 v[70:71], v[200:201]
	v_lshlrev_b32_e32 v68, 16, v70
	v_and_b32_e32 v69, 0xffff0000, v70
	v_lshlrev_b32_e32 v70, 16, v71
	v_and_b32_e32 v71, 0xffff0000, v71
	v_pk_add_f32 v[58:59], v[58:59], v[70:71]
	v_pk_add_f32 v[56:57], v[56:57], v[68:69]
	s_nop 0
	v_cvt_pk_bf16_f32 v68, v56, v57
	v_cvt_pk_bf16_f32 v69, v58, v59
	v_mul_f32_e32 v57, v57, v57
	global_store_dwordx2 v[66:67], v[68:69], off offset:32
	v_mul_f32_e32 v59, v59, v59
	v_fmac_f32_e32 v57, v56, v56
	v_fmac_f32_e32 v59, v58, v58
	v_add_f32_e32 v56, v57, v59
	v_add_f32_e32 v56, v60, v56
	v_mov_b64_e32 v[70:71], v[202:203]
	v_lshlrev_b32_e32 v68, 16, v70
	v_and_b32_e32 v69, 0xffff0000, v70
	v_lshlrev_b32_e32 v70, 16, v71
	v_and_b32_e32 v71, 0xffff0000, v71
	v_pk_add_f32 v[54:55], v[54:55], v[70:71]
	v_pk_add_f32 v[52:53], v[52:53], v[68:69]
	s_nop 0
	v_cvt_pk_bf16_f32 v68, v52, v53
	v_cvt_pk_bf16_f32 v69, v54, v55
	v_mul_f32_e32 v53, v53, v53
	v_mul_f32_e32 v55, v55, v55
	v_fmac_f32_e32 v53, v52, v52
	v_fmac_f32_e32 v55, v54, v54
	v_add_f32_e32 v52, v53, v55
	v_add_f32_e32 v56, v56, v52
	global_store_dwordx2 v[66:67], v[68:69], off offset:256
	v_mov_b64_e32 v[70:71], v[204:205]
	v_lshlrev_b32_e32 v52, 16, v70
	v_and_b32_e32 v53, 0xffff0000, v70
	v_lshlrev_b32_e32 v54, 16, v71
	v_and_b32_e32 v55, 0xffff0000, v71
	v_pk_add_f32 v[50:51], v[50:51], v[54:55]
	v_pk_add_f32 v[52:53], v[48:49], v[52:53]
	v_mul_f32_e32 v49, v51, v51
	v_mul_f32_e32 v48, v53, v53
	v_fmac_f32_e32 v48, v52, v52
	v_fmac_f32_e32 v49, v50, v50
	v_add_f32_e32 v48, v48, v49
	v_add_f32_e32 v48, v56, v48
	ds_bpermute_b32 v49, v149, v48
	v_cvt_pk_bf16_f32 v52, v52, v53
	v_cvt_pk_bf16_f32 v53, v50, v51
	global_store_dwordx2 v[66:67], v[52:53], off offset:288
	s_waitcnt lgkmcnt(0)
	v_add_f32_e32 v48, v48, v49
	ds_bpermute_b32 v49, v153, v48
	s_and_saveexec_b64 s[36:37], s[4:5]
	s_cbranch_execz .LBB0_1616
	s_waitcnt lgkmcnt(0)
	v_add_f32_e32 v50, v48, v49
	v_lshlrev_b64 v[48:49], 6, v[64:65]
	v_lshl_add_u64 v[48:49], s[60:61], 0, v[48:49]
	v_lshl_add_u64 v[48:49], s[30:31], 2, v[48:49]
	s_lshl_b32 s8, s50, 2
	v_lshl_add_u64 v[48:49], v[48:49], 0, s[8:9]
	global_store_dword v[48:49], v50, off
.LBB0_1616:
	s_or_b64 exec, exec, s[36:37]
	v_add_u32_e32 v48, 0x90, v144
	s_waitcnt lgkmcnt(0)
	v_ashrrev_i32_e32 v49, 31, v48
	v_lshlrev_b64 v[50:51], 11, v[48:49]
	v_lshl_add_u64 v[50:51], s[62:63], 0, v[50:51]
	v_lshl_add_u64 v[50:51], v[142:143], 1, v[50:51]
	v_mov_b64_e32 v[52:53], v[206:207]
	v_lshlrev_b32_e32 v54, 16, v52
	v_and_b32_e32 v55, 0xffff0000, v52
	v_lshlrev_b32_e32 v52, 16, v53
	v_and_b32_e32 v53, 0xffff0000, v53
	v_pk_add_f32 v[46:47], v[46:47], v[52:53]
	v_pk_add_f32 v[44:45], v[44:45], v[54:55]
	s_nop 0
	v_cvt_pk_bf16_f32 v52, v44, v45
	v_cvt_pk_bf16_f32 v53, v46, v47
	v_mul_f32_e32 v45, v45, v45
	global_store_dwordx2 v[50:51], v[52:53], off
	v_mul_f32_e32 v47, v47, v47
	v_fmac_f32_e32 v45, v44, v44
	v_fmac_f32_e32 v47, v46, v46
	v_add_f32_e32 v44, v45, v47
	v_mov_b64_e32 v[54:55], v[208:209]
	v_lshlrev_b32_e32 v52, 16, v54
	v_and_b32_e32 v53, 0xffff0000, v54
	v_lshlrev_b32_e32 v54, 16, v55
	v_and_b32_e32 v55, 0xffff0000, v55
	v_pk_add_f32 v[42:43], v[42:43], v[54:55]
	v_pk_add_f32 v[40:41], v[40:41], v[52:53]
	s_nop 0
	v_cvt_pk_bf16_f32 v52, v40, v41
	v_cvt_pk_bf16_f32 v53, v42, v43
	v_mul_f32_e32 v41, v41, v41
	global_store_dwordx2 v[50:51], v[52:53], off offset:32
	v_mul_f32_e32 v43, v43, v43
	v_fmac_f32_e32 v41, v40, v40
	v_fmac_f32_e32 v43, v42, v42
	v_add_f32_e32 v40, v41, v43
	v_add_f32_e32 v40, v44, v40
	v_mov_b64_e32 v[54:55], v[210:211]
	v_lshlrev_b32_e32 v52, 16, v54
	v_and_b32_e32 v53, 0xffff0000, v54
	v_lshlrev_b32_e32 v54, 16, v55
	v_and_b32_e32 v55, 0xffff0000, v55
	v_pk_add_f32 v[38:39], v[38:39], v[54:55]
	v_pk_add_f32 v[36:37], v[36:37], v[52:53]
	s_nop 0
	v_cvt_pk_bf16_f32 v52, v36, v37
	v_cvt_pk_bf16_f32 v53, v38, v39
	v_mul_f32_e32 v37, v37, v37
	v_mul_f32_e32 v39, v39, v39
	v_fmac_f32_e32 v37, v36, v36
	v_fmac_f32_e32 v39, v38, v38
	v_add_f32_e32 v36, v37, v39
	v_add_f32_e32 v40, v40, v36
	global_store_dwordx2 v[50:51], v[52:53], off offset:256
	v_mov_b64_e32 v[54:55], v[212:213]
	v_lshlrev_b32_e32 v36, 16, v54
	v_and_b32_e32 v37, 0xffff0000, v54
	v_lshlrev_b32_e32 v38, 16, v55
	v_and_b32_e32 v39, 0xffff0000, v55
	v_pk_add_f32 v[34:35], v[34:35], v[38:39]
	v_pk_add_f32 v[36:37], v[32:33], v[36:37]
	v_mul_f32_e32 v33, v35, v35
	v_mul_f32_e32 v32, v37, v37
	v_fmac_f32_e32 v32, v36, v36
	v_fmac_f32_e32 v33, v34, v34
	v_add_f32_e32 v32, v32, v33
	v_add_f32_e32 v32, v40, v32
	ds_bpermute_b32 v33, v149, v32
	v_cvt_pk_bf16_f32 v36, v36, v37
	v_cvt_pk_bf16_f32 v37, v34, v35
	global_store_dwordx2 v[50:51], v[36:37], off offset:288
	s_waitcnt lgkmcnt(0)
	v_add_f32_e32 v32, v32, v33
	ds_bpermute_b32 v33, v153, v32
	s_and_saveexec_b64 s[36:37], s[4:5]
	s_cbranch_execz .LBB0_1618
	s_waitcnt lgkmcnt(0)
	v_add_f32_e32 v34, v32, v33
	v_lshlrev_b64 v[32:33], 6, v[48:49]
	v_lshl_add_u64 v[32:33], s[60:61], 0, v[32:33]
	v_lshl_add_u64 v[32:33], s[30:31], 2, v[32:33]
	s_lshl_b32 s8, s50, 2
	v_lshl_add_u64 v[32:33], v[32:33], 0, s[8:9]
	global_store_dword v[32:33], v34, off
.LBB0_1618:
	s_or_b64 exec, exec, s[36:37]
	v_add_u32_e32 v32, 0xa0, v144
	s_waitcnt lgkmcnt(0)
	v_ashrrev_i32_e32 v33, 31, v32
	v_lshlrev_b64 v[34:35], 11, v[32:33]
	v_lshl_add_u64 v[34:35], s[62:63], 0, v[34:35]
	v_lshl_add_u64 v[34:35], v[142:143], 1, v[34:35]
	v_mov_b64_e32 v[36:37], v[214:215]
	v_lshlrev_b32_e32 v38, 16, v36
	v_and_b32_e32 v39, 0xffff0000, v36
	v_lshlrev_b32_e32 v36, 16, v37
	v_and_b32_e32 v37, 0xffff0000, v37
	v_pk_add_f32 v[30:31], v[30:31], v[36:37]
	v_pk_add_f32 v[28:29], v[28:29], v[38:39]
	s_nop 0
	v_cvt_pk_bf16_f32 v36, v28, v29
	v_cvt_pk_bf16_f32 v37, v30, v31
	v_mul_f32_e32 v29, v29, v29
	global_store_dwordx2 v[34:35], v[36:37], off
	v_mul_f32_e32 v31, v31, v31
	v_fmac_f32_e32 v29, v28, v28
	v_fmac_f32_e32 v31, v30, v30
	v_add_f32_e32 v28, v29, v31
	v_mov_b64_e32 v[38:39], v[216:217]
	v_lshlrev_b32_e32 v36, 16, v38
	v_and_b32_e32 v37, 0xffff0000, v38
	v_lshlrev_b32_e32 v38, 16, v39
	v_and_b32_e32 v39, 0xffff0000, v39
	v_pk_add_f32 v[26:27], v[26:27], v[38:39]
	v_pk_add_f32 v[24:25], v[24:25], v[36:37]
	s_nop 0
	v_cvt_pk_bf16_f32 v36, v24, v25
	v_cvt_pk_bf16_f32 v37, v26, v27
	v_mul_f32_e32 v25, v25, v25
	global_store_dwordx2 v[34:35], v[36:37], off offset:32
	v_mul_f32_e32 v27, v27, v27
	v_fmac_f32_e32 v25, v24, v24
	v_fmac_f32_e32 v27, v26, v26
	v_add_f32_e32 v24, v25, v27
	v_add_f32_e32 v24, v28, v24
	v_mov_b64_e32 v[38:39], v[218:219]
	v_lshlrev_b32_e32 v36, 16, v38
	v_and_b32_e32 v37, 0xffff0000, v38
	v_lshlrev_b32_e32 v38, 16, v39
	v_and_b32_e32 v39, 0xffff0000, v39
	v_pk_add_f32 v[22:23], v[22:23], v[38:39]
	v_pk_add_f32 v[20:21], v[20:21], v[36:37]
	s_nop 0
	v_cvt_pk_bf16_f32 v36, v20, v21
	v_cvt_pk_bf16_f32 v37, v22, v23
	v_mul_f32_e32 v21, v21, v21
	v_mul_f32_e32 v23, v23, v23
	v_fmac_f32_e32 v21, v20, v20
	v_fmac_f32_e32 v23, v22, v22
	v_add_f32_e32 v20, v21, v23
	v_add_f32_e32 v24, v24, v20
	global_store_dwordx2 v[34:35], v[36:37], off offset:256
	v_mov_b64_e32 v[38:39], v[220:221]
	v_lshlrev_b32_e32 v20, 16, v38
	v_and_b32_e32 v21, 0xffff0000, v38
	v_lshlrev_b32_e32 v22, 16, v39
	v_and_b32_e32 v23, 0xffff0000, v39
	v_pk_add_f32 v[18:19], v[18:19], v[22:23]
	v_pk_add_f32 v[20:21], v[16:17], v[20:21]
	v_mul_f32_e32 v17, v19, v19
	v_mul_f32_e32 v16, v21, v21
	v_fmac_f32_e32 v16, v20, v20
	v_fmac_f32_e32 v17, v18, v18
	v_add_f32_e32 v16, v16, v17
	v_add_f32_e32 v16, v24, v16
	ds_bpermute_b32 v17, v149, v16
	v_cvt_pk_bf16_f32 v20, v20, v21
	v_cvt_pk_bf16_f32 v21, v18, v19
	global_store_dwordx2 v[34:35], v[20:21], off offset:288
	s_waitcnt lgkmcnt(0)
	v_add_f32_e32 v16, v16, v17
	ds_bpermute_b32 v17, v153, v16
	s_and_saveexec_b64 s[36:37], s[4:5]
	s_cbranch_execz .LBB0_1620
	s_waitcnt lgkmcnt(0)
	v_add_f32_e32 v18, v16, v17
	v_lshlrev_b64 v[16:17], 6, v[32:33]
	v_lshl_add_u64 v[16:17], s[60:61], 0, v[16:17]
	v_lshl_add_u64 v[16:17], s[30:31], 2, v[16:17]
	s_lshl_b32 s8, s50, 2
	v_lshl_add_u64 v[16:17], v[16:17], 0, s[8:9]
	global_store_dword v[16:17], v18, off
.LBB0_1620:
	s_or_b64 exec, exec, s[36:37]
	v_add_u32_e32 v16, 0xb0, v144
	s_waitcnt lgkmcnt(0)
	v_ashrrev_i32_e32 v17, 31, v16
	v_lshlrev_b64 v[18:19], 11, v[16:17]
	v_lshl_add_u64 v[18:19], s[62:63], 0, v[18:19]
	v_lshl_add_u64 v[18:19], v[142:143], 1, v[18:19]
	v_mov_b64_e32 v[20:21], v[222:223]
	v_lshlrev_b32_e32 v22, 16, v20
	v_and_b32_e32 v23, 0xffff0000, v20
	v_lshlrev_b32_e32 v20, 16, v21
	v_and_b32_e32 v21, 0xffff0000, v21
	v_pk_add_f32 v[14:15], v[14:15], v[20:21]
	v_pk_add_f32 v[12:13], v[12:13], v[22:23]
	s_nop 0
	v_cvt_pk_bf16_f32 v20, v12, v13
	v_cvt_pk_bf16_f32 v21, v14, v15
	v_mul_f32_e32 v13, v13, v13
	global_store_dwordx2 v[18:19], v[20:21], off
	v_mul_f32_e32 v15, v15, v15
	v_fmac_f32_e32 v13, v12, v12
	v_fmac_f32_e32 v15, v14, v14
	v_add_f32_e32 v12, v13, v15
	v_mov_b64_e32 v[22:23], v[224:225]
	v_lshlrev_b32_e32 v20, 16, v22
	v_and_b32_e32 v21, 0xffff0000, v22
	v_lshlrev_b32_e32 v22, 16, v23
	v_and_b32_e32 v23, 0xffff0000, v23
	v_pk_add_f32 v[10:11], v[10:11], v[22:23]
	v_pk_add_f32 v[8:9], v[8:9], v[20:21]
	s_nop 0
	v_cvt_pk_bf16_f32 v20, v8, v9
	v_cvt_pk_bf16_f32 v21, v10, v11
	v_mul_f32_e32 v9, v9, v9
	global_store_dwordx2 v[18:19], v[20:21], off offset:32
	v_mul_f32_e32 v11, v11, v11
	v_fmac_f32_e32 v9, v8, v8
	v_fmac_f32_e32 v11, v10, v10
	v_add_f32_e32 v8, v9, v11
	v_add_f32_e32 v8, v12, v8
	v_mov_b64_e32 v[22:23], v[226:227]
	v_lshlrev_b32_e32 v20, 16, v22
	v_and_b32_e32 v21, 0xffff0000, v22
	v_lshlrev_b32_e32 v22, 16, v23
	v_and_b32_e32 v23, 0xffff0000, v23
	v_pk_add_f32 v[6:7], v[6:7], v[22:23]
	v_pk_add_f32 v[4:5], v[4:5], v[20:21]
	s_nop 0
	v_cvt_pk_bf16_f32 v20, v4, v5
	v_cvt_pk_bf16_f32 v21, v6, v7
	v_mul_f32_e32 v5, v5, v5
	v_mul_f32_e32 v7, v7, v7
	v_fmac_f32_e32 v5, v4, v4
	v_fmac_f32_e32 v7, v6, v6
	v_add_f32_e32 v4, v5, v7
	v_add_f32_e32 v8, v8, v4
	global_store_dwordx2 v[18:19], v[20:21], off offset:256
	v_mov_b64_e32 v[22:23], v[228:229]
	v_lshlrev_b32_e32 v4, 16, v22
	v_and_b32_e32 v5, 0xffff0000, v22
	v_lshlrev_b32_e32 v6, 16, v23
	v_and_b32_e32 v7, 0xffff0000, v23
	v_pk_add_f32 v[2:3], v[2:3], v[6:7]
	v_pk_add_f32 v[4:5], v[0:1], v[4:5]
	v_mul_f32_e32 v1, v3, v3
	v_mul_f32_e32 v0, v5, v5
	v_fmac_f32_e32 v0, v4, v4
	v_fmac_f32_e32 v1, v2, v2
	v_add_f32_e32 v0, v0, v1
	v_add_f32_e32 v0, v8, v0
	ds_bpermute_b32 v1, v149, v0
	v_cvt_pk_bf16_f32 v4, v4, v5
	v_cvt_pk_bf16_f32 v5, v2, v3
	global_store_dwordx2 v[18:19], v[4:5], off offset:288
	s_waitcnt lgkmcnt(0)
	v_add_f32_e32 v0, v0, v1
	ds_bpermute_b32 v1, v153, v0
	s_and_saveexec_b64 s[36:37], s[4:5]
	s_cbranch_execz .LBB0_1622
	s_waitcnt lgkmcnt(0)
	v_add_f32_e32 v2, v0, v1
	v_lshlrev_b64 v[0:1], 6, v[16:17]
	v_lshl_add_u64 v[0:1], s[60:61], 0, v[0:1]
	v_lshl_add_u64 v[0:1], s[30:31], 2, v[0:1]
	s_lshl_b32 s8, s50, 2
	v_lshl_add_u64 v[0:1], v[0:1], 0, s[8:9]
	global_store_dword v[0:1], v2, off

.LBB0_1827:
	v_lshl_add_u32 v144, s51, 8, v133
	s_lshl_b32 s22, s10, 8
	v_ashrrev_i32_e32 v145, 31, v144
	s_ashr_i32 s23, s22, 31
	v_lshlrev_b64 v[154:155], 11, v[144:145]
	v_mov_b32_e32 v143, s23
	v_or_b32_e32 v142, s22, v132
	v_lshl_add_u64 v[154:155], s[62:63], 0, v[154:155]
	v_lshl_add_u64 v[154:155], v[142:143], 1, v[154:155]
	global_load_dwordx2 v[164:165], v[154:155], off
	global_load_dwordx2 v[166:167], v[154:155], off offset:32
	global_load_dwordx2 v[168:169], v[154:155], off offset:256
	global_load_dwordx2 v[170:171], v[154:155], off offset:288
	v_add_co_u32_e32 v230, vcc, 0x8000, v154
	s_nop 1
	v_addc_co_u32_e32 v231, vcc, 0, v155, vcc
	global_load_dwordx2 v[172:173], v[230:231], off
	global_load_dwordx2 v[174:175], v[230:231], off offset:32
	global_load_dwordx2 v[176:177], v[230:231], off offset:256
	global_load_dwordx2 v[178:179], v[230:231], off offset:288
	v_add_co_u32_e32 v230, vcc, 0x10000, v154
	s_nop 1
	v_addc_co_u32_e32 v231, vcc, 0, v155, vcc
	global_load_dwordx2 v[180:181], v[230:231], off
	global_load_dwordx2 v[182:183], v[230:231], off offset:32
	global_load_dwordx2 v[184:185], v[230:231], off offset:256
	global_load_dwordx2 v[188:189], v[230:231], off offset:288
	v_add_co_u32_e32 v230, vcc, 0x18000, v154
	s_nop 1
	v_addc_co_u32_e32 v231, vcc, 0, v155, vcc
	global_load_dwordx2 v[190:191], v[230:231], off
	global_load_dwordx2 v[192:193], v[230:231], off offset:32
	global_load_dwordx2 v[194:195], v[230:231], off offset:256
	global_load_dwordx2 v[196:197], v[230:231], off offset:288
	v_add_co_u32_e32 v230, vcc, 0x40000, v154
	s_nop 1
	v_addc_co_u32_e32 v231, vcc, 0, v155, vcc
	global_load_dwordx2 v[198:199], v[230:231], off
	global_load_dwordx2 v[200:201], v[230:231], off offset:32
	global_load_dwordx2 v[202:203], v[230:231], off offset:256
	global_load_dwordx2 v[204:205], v[230:231], off offset:288
	v_add_co_u32_e32 v230, vcc, 0x48000, v154
	s_nop 1
	v_addc_co_u32_e32 v231, vcc, 0, v155, vcc
	global_load_dwordx2 v[206:207], v[230:231], off
	global_load_dwordx2 v[208:209], v[230:231], off offset:32
	global_load_dwordx2 v[210:211], v[230:231], off offset:256
	global_load_dwordx2 v[212:213], v[230:231], off offset:288
	v_add_co_u32_e32 v230, vcc, 0x50000, v154
	s_nop 1
	v_addc_co_u32_e32 v231, vcc, 0, v155, vcc
	global_load_dwordx2 v[214:215], v[230:231], off
	global_load_dwordx2 v[216:217], v[230:231], off offset:32
	global_load_dwordx2 v[218:219], v[230:231], off offset:256
	global_load_dwordx2 v[220:221], v[230:231], off offset:288
	v_add_co_u32_e32 v230, vcc, 0x58000, v154
	s_nop 1
	v_addc_co_u32_e32 v231, vcc, 0, v155, vcc
	global_load_dwordx2 v[222:223], v[230:231], off
	global_load_dwordx2 v[224:225], v[230:231], off offset:32
	global_load_dwordx2 v[226:227], v[230:231], off offset:256
	global_load_dwordx2 v[228:229], v[230:231], off offset:288
	s_waitcnt vmcnt(0)
	s_lshl_b32 s22, s10, 2
	s_ashr_i32 s23, s22, 31
	v_mov_b64_e32 v[156:157], v[164:165]
	v_lshlrev_b32_e32 v158, 16, v156
	v_and_b32_e32 v159, 0xffff0000, v156
	v_lshlrev_b32_e32 v156, 16, v157
	v_and_b32_e32 v157, 0xffff0000, v157
	v_pk_add_f32 v[126:127], v[126:127], v[156:157]
	v_pk_add_f32 v[124:125], v[124:125], v[158:159]
	s_nop 0
	v_cvt_pk_bf16_f32 v156, v124, v125
	v_cvt_pk_bf16_f32 v157, v126, v127
	v_mul_f32_e32 v125, v125, v125
	global_store_dwordx2 v[154:155], v[156:157], off
	v_mul_f32_e32 v127, v127, v127
	v_fmac_f32_e32 v125, v124, v124
	v_fmac_f32_e32 v127, v126, v126
	v_add_f32_e32 v124, v125, v127
	v_mov_b64_e32 v[158:159], v[166:167]
	v_lshlrev_b32_e32 v156, 16, v158
	v_and_b32_e32 v157, 0xffff0000, v158
	v_lshlrev_b32_e32 v158, 16, v159
	v_and_b32_e32 v159, 0xffff0000, v159
	v_pk_add_f32 v[122:123], v[122:123], v[158:159]
	v_pk_add_f32 v[120:121], v[120:121], v[156:157]
	s_nop 0
	v_cvt_pk_bf16_f32 v156, v120, v121
	v_cvt_pk_bf16_f32 v157, v122, v123
	v_mul_f32_e32 v121, v121, v121
	global_store_dwordx2 v[154:155], v[156:157], off offset:32
	v_mul_f32_e32 v123, v123, v123
	v_fmac_f32_e32 v121, v120, v120
	v_fmac_f32_e32 v123, v122, v122
	v_add_f32_e32 v120, v121, v123
	v_add_f32_e32 v120, v124, v120
	v_mov_b64_e32 v[158:159], v[168:169]
	v_lshlrev_b32_e32 v156, 16, v158
	v_and_b32_e32 v157, 0xffff0000, v158
	v_lshlrev_b32_e32 v158, 16, v159
	v_and_b32_e32 v159, 0xffff0000, v159
	v_pk_add_f32 v[118:119], v[118:119], v[158:159]
	v_pk_add_f32 v[116:117], v[116:117], v[156:157]
	s_nop 0
	v_cvt_pk_bf16_f32 v156, v116, v117
	v_cvt_pk_bf16_f32 v157, v118, v119
	v_mul_f32_e32 v117, v117, v117
	v_mul_f32_e32 v119, v119, v119
	v_fmac_f32_e32 v117, v116, v116
	v_fmac_f32_e32 v119, v118, v118
	v_add_f32_e32 v116, v117, v119
	v_add_f32_e32 v120, v120, v116
	global_store_dwordx2 v[154:155], v[156:157], off offset:256
	v_mov_b64_e32 v[158:159], v[170:171]
	v_lshlrev_b32_e32 v116, 16, v158
	v_and_b32_e32 v117, 0xffff0000, v158
	v_lshlrev_b32_e32 v118, 16, v159
	v_and_b32_e32 v119, 0xffff0000, v159
	v_pk_add_f32 v[114:115], v[114:115], v[118:119]
	v_pk_add_f32 v[116:117], v[112:113], v[116:117]
	v_mul_f32_e32 v113, v115, v115
	v_mul_f32_e32 v112, v117, v117
	v_fmac_f32_e32 v112, v116, v116
	v_fmac_f32_e32 v113, v114, v114
	v_add_f32_e32 v112, v112, v113
	v_add_f32_e32 v112, v120, v112
	ds_bpermute_b32 v113, v149, v112
	v_cvt_pk_bf16_f32 v116, v116, v117
	v_cvt_pk_bf16_f32 v117, v114, v115
	global_store_dwordx2 v[154:155], v[116:117], off offset:288
	s_waitcnt lgkmcnt(0)
	v_add_f32_e32 v112, v112, v113
	ds_bpermute_b32 v113, v153, v112
	s_and_saveexec_b64 s[24:25], s[8:9]
	s_cbranch_execz .LBB0_1829
	s_waitcnt lgkmcnt(0)
	v_add_f32_e32 v114, v112, v113
	v_lshlrev_b64 v[112:113], 6, v[144:145]
	v_lshl_add_u64 v[112:113], s[60:61], 0, v[112:113]
	v_lshl_add_u64 v[112:113], s[22:23], 2, v[112:113]
	s_lshl_b32 s10, s40, 2
	v_lshl_add_u64 v[112:113], v[112:113], 0, s[10:11]
	global_store_dword v[112:113], v114, off
.LBB0_1829:
	s_or_b64 exec, exec, s[24:25]
	v_or_b32_e32 v112, 16, v144
	s_waitcnt lgkmcnt(0)
	v_ashrrev_i32_e32 v113, 31, v112
	v_lshlrev_b64 v[114:115], 11, v[112:113]
	v_lshl_add_u64 v[114:115], s[62:63], 0, v[114:115]
	v_lshl_add_u64 v[114:115], v[142:143], 1, v[114:115]
	v_mov_b64_e32 v[116:117], v[172:173]
	v_lshlrev_b32_e32 v118, 16, v116
	v_and_b32_e32 v119, 0xffff0000, v116
	v_lshlrev_b32_e32 v116, 16, v117
	v_and_b32_e32 v117, 0xffff0000, v117
	v_pk_add_f32 v[110:111], v[110:111], v[116:117]
	v_pk_add_f32 v[108:109], v[108:109], v[118:119]
	s_nop 0
	v_cvt_pk_bf16_f32 v116, v108, v109
	v_cvt_pk_bf16_f32 v117, v110, v111
	v_mul_f32_e32 v109, v109, v109
	global_store_dwordx2 v[114:115], v[116:117], off
	v_mul_f32_e32 v111, v111, v111
	v_fmac_f32_e32 v109, v108, v108
	v_fmac_f32_e32 v111, v110, v110
	v_add_f32_e32 v108, v109, v111
	v_mov_b64_e32 v[118:119], v[174:175]
	v_lshlrev_b32_e32 v116, 16, v118
	v_and_b32_e32 v117, 0xffff0000, v118
	v_lshlrev_b32_e32 v118, 16, v119
	v_and_b32_e32 v119, 0xffff0000, v119
	v_pk_add_f32 v[106:107], v[106:107], v[118:119]
	v_pk_add_f32 v[104:105], v[104:105], v[116:117]
	s_nop 0
	v_cvt_pk_bf16_f32 v116, v104, v105
	v_cvt_pk_bf16_f32 v117, v106, v107
	v_mul_f32_e32 v105, v105, v105
	global_store_dwordx2 v[114:115], v[116:117], off offset:32
	v_mul_f32_e32 v107, v107, v107
	v_fmac_f32_e32 v105, v104, v104
	v_fmac_f32_e32 v107, v106, v106
	v_add_f32_e32 v104, v105, v107
	v_add_f32_e32 v104, v108, v104
	v_mov_b64_e32 v[118:119], v[176:177]
	v_lshlrev_b32_e32 v116, 16, v118
	v_and_b32_e32 v117, 0xffff0000, v118
	v_lshlrev_b32_e32 v118, 16, v119
	v_and_b32_e32 v119, 0xffff0000, v119
	v_pk_add_f32 v[102:103], v[102:103], v[118:119]
	v_pk_add_f32 v[100:101], v[100:101], v[116:117]
	s_nop 0
	v_cvt_pk_bf16_f32 v116, v100, v101
	v_cvt_pk_bf16_f32 v117, v102, v103
	v_mul_f32_e32 v101, v101, v101
	v_mul_f32_e32 v103, v103, v103
	v_fmac_f32_e32 v101, v100, v100
	v_fmac_f32_e32 v103, v102, v102
	v_add_f32_e32 v100, v101, v103
	v_add_f32_e32 v104, v104, v100
	global_store_dwordx2 v[114:115], v[116:117], off offset:256
	v_mov_b64_e32 v[118:119], v[178:179]
	v_lshlrev_b32_e32 v100, 16, v118
	v_and_b32_e32 v101, 0xffff0000, v118
	v_lshlrev_b32_e32 v102, 16, v119
	v_and_b32_e32 v103, 0xffff0000, v119
	v_pk_add_f32 v[98:99], v[98:99], v[102:103]
	v_pk_add_f32 v[100:101], v[96:97], v[100:101]
	v_mul_f32_e32 v97, v99, v99
	v_mul_f32_e32 v96, v101, v101
	v_fmac_f32_e32 v96, v100, v100
	v_fmac_f32_e32 v97, v98, v98
	v_add_f32_e32 v96, v96, v97
	v_add_f32_e32 v96, v104, v96
	ds_bpermute_b32 v97, v149, v96
	v_cvt_pk_bf16_f32 v100, v100, v101
	v_cvt_pk_bf16_f32 v101, v98, v99
	global_store_dwordx2 v[114:115], v[100:101], off offset:288
	s_waitcnt lgkmcnt(0)
	v_add_f32_e32 v96, v96, v97
	ds_bpermute_b32 v97, v153, v96
	s_and_saveexec_b64 s[24:25], s[8:9]
	s_cbranch_execz .LBB0_1831
	s_waitcnt lgkmcnt(0)
	v_add_f32_e32 v98, v96, v97
	v_lshlrev_b64 v[96:97], 6, v[112:113]
	v_lshl_add_u64 v[96:97], s[60:61], 0, v[96:97]
	v_lshl_add_u64 v[96:97], s[22:23], 2, v[96:97]
	s_lshl_b32 s10, s40, 2
	v_lshl_add_u64 v[96:97], v[96:97], 0, s[10:11]
	global_store_dword v[96:97], v98, off
.LBB0_1831:
	s_or_b64 exec, exec, s[24:25]
	v_or_b32_e32 v96, 32, v144
	s_waitcnt lgkmcnt(0)
	v_ashrrev_i32_e32 v97, 31, v96
	v_lshlrev_b64 v[98:99], 11, v[96:97]
	v_lshl_add_u64 v[98:99], s[62:63], 0, v[98:99]
	v_lshl_add_u64 v[98:99], v[142:143], 1, v[98:99]
	v_mov_b64_e32 v[100:101], v[180:181]
	v_lshlrev_b32_e32 v102, 16, v100
	v_and_b32_e32 v103, 0xffff0000, v100
	v_lshlrev_b32_e32 v100, 16, v101
	v_and_b32_e32 v101, 0xffff0000, v101
	v_pk_add_f32 v[94:95], v[94:95], v[100:101]
	v_pk_add_f32 v[92:93], v[92:93], v[102:103]
	s_nop 0
	v_cvt_pk_bf16_f32 v100, v92, v93
	v_cvt_pk_bf16_f32 v101, v94, v95
	v_mul_f32_e32 v93, v93, v93
	global_store_dwordx2 v[98:99], v[100:101], off
	v_mul_f32_e32 v95, v95, v95
	v_fmac_f32_e32 v93, v92, v92
	v_fmac_f32_e32 v95, v94, v94
	v_add_f32_e32 v92, v93, v95
	v_mov_b64_e32 v[102:103], v[182:183]
	v_lshlrev_b32_e32 v100, 16, v102
	v_and_b32_e32 v101, 0xffff0000, v102
	v_lshlrev_b32_e32 v102, 16, v103
	v_and_b32_e32 v103, 0xffff0000, v103
	v_pk_add_f32 v[90:91], v[90:91], v[102:103]
	v_pk_add_f32 v[88:89], v[88:89], v[100:101]
	s_nop 0
	v_cvt_pk_bf16_f32 v100, v88, v89
	v_cvt_pk_bf16_f32 v101, v90, v91
	v_mul_f32_e32 v89, v89, v89
	global_store_dwordx2 v[98:99], v[100:101], off offset:32
	v_mul_f32_e32 v91, v91, v91
	v_fmac_f32_e32 v89, v88, v88
	v_fmac_f32_e32 v91, v90, v90
	v_add_f32_e32 v88, v89, v91
	v_add_f32_e32 v88, v92, v88
	v_mov_b64_e32 v[102:103], v[184:185]
	v_lshlrev_b32_e32 v100, 16, v102
	v_and_b32_e32 v101, 0xffff0000, v102
	v_lshlrev_b32_e32 v102, 16, v103
	v_and_b32_e32 v103, 0xffff0000, v103
	v_pk_add_f32 v[86:87], v[86:87], v[102:103]
	v_pk_add_f32 v[84:85], v[84:85], v[100:101]
	s_nop 0
	v_cvt_pk_bf16_f32 v100, v84, v85
	v_cvt_pk_bf16_f32 v101, v86, v87
	v_mul_f32_e32 v85, v85, v85
	v_mul_f32_e32 v87, v87, v87
	v_fmac_f32_e32 v85, v84, v84
	v_fmac_f32_e32 v87, v86, v86
	v_add_f32_e32 v84, v85, v87
	v_add_f32_e32 v88, v88, v84
	global_store_dwordx2 v[98:99], v[100:101], off offset:256
	v_mov_b64_e32 v[102:103], v[188:189]
	v_lshlrev_b32_e32 v84, 16, v102
	v_and_b32_e32 v85, 0xffff0000, v102
	v_lshlrev_b32_e32 v86, 16, v103
	v_and_b32_e32 v87, 0xffff0000, v103
	v_pk_add_f32 v[82:83], v[82:83], v[86:87]
	v_pk_add_f32 v[84:85], v[80:81], v[84:85]
	v_mul_f32_e32 v81, v83, v83
	v_mul_f32_e32 v80, v85, v85
	v_fmac_f32_e32 v80, v84, v84
	v_fmac_f32_e32 v81, v82, v82
	v_add_f32_e32 v80, v80, v81
	v_add_f32_e32 v80, v88, v80
	ds_bpermute_b32 v81, v149, v80
	v_cvt_pk_bf16_f32 v84, v84, v85
	v_cvt_pk_bf16_f32 v85, v82, v83
	global_store_dwordx2 v[98:99], v[84:85], off offset:288
	s_waitcnt lgkmcnt(0)
	v_add_f32_e32 v80, v80, v81
	ds_bpermute_b32 v81, v153, v80
	s_and_saveexec_b64 s[24:25], s[8:9]
	s_cbranch_execz .LBB0_1833
	s_waitcnt lgkmcnt(0)
	v_add_f32_e32 v82, v80, v81
	v_lshlrev_b64 v[80:81], 6, v[96:97]
	v_lshl_add_u64 v[80:81], s[60:61], 0, v[80:81]
	v_lshl_add_u64 v[80:81], s[22:23], 2, v[80:81]
	s_lshl_b32 s10, s40, 2
	v_lshl_add_u64 v[80:81], v[80:81], 0, s[10:11]
	global_store_dword v[80:81], v82, off
.LBB0_1833:
	s_or_b64 exec, exec, s[24:25]
	v_or_b32_e32 v80, 48, v144
	s_waitcnt lgkmcnt(0)
	v_ashrrev_i32_e32 v81, 31, v80
	v_lshlrev_b64 v[82:83], 11, v[80:81]
	v_lshl_add_u64 v[82:83], s[62:63], 0, v[82:83]
	v_lshl_add_u64 v[82:83], v[142:143], 1, v[82:83]
	v_mov_b64_e32 v[84:85], v[190:191]
	v_lshlrev_b32_e32 v86, 16, v84
	v_and_b32_e32 v87, 0xffff0000, v84
	v_lshlrev_b32_e32 v84, 16, v85
	v_and_b32_e32 v85, 0xffff0000, v85
	v_pk_add_f32 v[78:79], v[78:79], v[84:85]
	v_pk_add_f32 v[76:77], v[76:77], v[86:87]
	s_nop 0
	v_cvt_pk_bf16_f32 v84, v76, v77
	v_cvt_pk_bf16_f32 v85, v78, v79
	v_mul_f32_e32 v77, v77, v77
	global_store_dwordx2 v[82:83], v[84:85], off
	v_mul_f32_e32 v79, v79, v79
	v_fmac_f32_e32 v77, v76, v76
	v_fmac_f32_e32 v79, v78, v78
	v_add_f32_e32 v76, v77, v79
	v_mov_b64_e32 v[86:87], v[192:193]
	v_lshlrev_b32_e32 v84, 16, v86
	v_and_b32_e32 v85, 0xffff0000, v86
	v_lshlrev_b32_e32 v86, 16, v87
	v_and_b32_e32 v87, 0xffff0000, v87
	v_pk_add_f32 v[74:75], v[74:75], v[86:87]
	v_pk_add_f32 v[72:73], v[72:73], v[84:85]
	s_nop 0
	v_cvt_pk_bf16_f32 v84, v72, v73
	v_cvt_pk_bf16_f32 v85, v74, v75
	v_mul_f32_e32 v73, v73, v73
	global_store_dwordx2 v[82:83], v[84:85], off offset:32
	v_mul_f32_e32 v75, v75, v75
	v_fmac_f32_e32 v73, v72, v72
	v_fmac_f32_e32 v75, v74, v74
	v_add_f32_e32 v72, v73, v75
	v_add_f32_e32 v72, v76, v72
	v_mov_b64_e32 v[86:87], v[194:195]
	v_lshlrev_b32_e32 v84, 16, v86
	v_and_b32_e32 v85, 0xffff0000, v86
	v_lshlrev_b32_e32 v86, 16, v87
	v_and_b32_e32 v87, 0xffff0000, v87
	v_pk_add_f32 v[70:71], v[70:71], v[86:87]
	v_pk_add_f32 v[68:69], v[68:69], v[84:85]
	s_nop 0
	v_cvt_pk_bf16_f32 v84, v68, v69
	v_cvt_pk_bf16_f32 v85, v70, v71
	v_mul_f32_e32 v69, v69, v69
	v_mul_f32_e32 v71, v71, v71
	v_fmac_f32_e32 v69, v68, v68
	v_fmac_f32_e32 v71, v70, v70
	v_add_f32_e32 v68, v69, v71
	v_add_f32_e32 v72, v72, v68
	global_store_dwordx2 v[82:83], v[84:85], off offset:256
	v_mov_b64_e32 v[86:87], v[196:197]
	v_lshlrev_b32_e32 v68, 16, v86
	v_and_b32_e32 v69, 0xffff0000, v86
	v_lshlrev_b32_e32 v70, 16, v87
	v_and_b32_e32 v71, 0xffff0000, v87
	v_pk_add_f32 v[66:67], v[66:67], v[70:71]
	v_pk_add_f32 v[68:69], v[64:65], v[68:69]
	v_mul_f32_e32 v65, v67, v67
	v_mul_f32_e32 v64, v69, v69
	v_fmac_f32_e32 v64, v68, v68
	v_fmac_f32_e32 v65, v66, v66
	v_add_f32_e32 v64, v64, v65
	v_add_f32_e32 v64, v72, v64
	ds_bpermute_b32 v65, v149, v64
	v_cvt_pk_bf16_f32 v68, v68, v69
	v_cvt_pk_bf16_f32 v69, v66, v67
	global_store_dwordx2 v[82:83], v[68:69], off offset:288
	s_waitcnt lgkmcnt(0)
	v_add_f32_e32 v64, v64, v65
	ds_bpermute_b32 v65, v153, v64
	s_and_saveexec_b64 s[24:25], s[8:9]
	s_cbranch_execz .LBB0_1835
	s_waitcnt lgkmcnt(0)
	v_add_f32_e32 v66, v64, v65
	v_lshlrev_b64 v[64:65], 6, v[80:81]
	v_lshl_add_u64 v[64:65], s[60:61], 0, v[64:65]
	v_lshl_add_u64 v[64:65], s[22:23], 2, v[64:65]
	s_lshl_b32 s10, s40, 2
	v_lshl_add_u64 v[64:65], v[64:65], 0, s[10:11]
	global_store_dword v[64:65], v66, off
.LBB0_1835:
	s_or_b64 exec, exec, s[24:25]
	v_add_u32_e32 v64, 0x80, v144
	s_waitcnt lgkmcnt(0)
	v_ashrrev_i32_e32 v65, 31, v64
	v_lshlrev_b64 v[66:67], 11, v[64:65]
	v_lshl_add_u64 v[66:67], s[62:63], 0, v[66:67]
	v_lshl_add_u64 v[66:67], v[142:143], 1, v[66:67]
	v_mov_b64_e32 v[68:69], v[198:199]
	v_lshlrev_b32_e32 v70, 16, v68
	v_and_b32_e32 v71, 0xffff0000, v68
	v_lshlrev_b32_e32 v68, 16, v69
	v_and_b32_e32 v69, 0xffff0000, v69
	v_pk_add_f32 v[62:63], v[62:63], v[68:69]
	v_pk_add_f32 v[60:61], v[60:61], v[70:71]
	s_nop 0
	v_cvt_pk_bf16_f32 v68, v60, v61
	v_cvt_pk_bf16_f32 v69, v62, v63
	v_mul_f32_e32 v61, v61, v61
	global_store_dwordx2 v[66:67], v[68:69], off
	v_mul_f32_e32 v63, v63, v63
	v_fmac_f32_e32 v61, v60, v60
	v_fmac_f32_e32 v63, v62, v62
	v_add_f32_e32 v60, v61, v63
	v_mov_b64_e32 v[70:71], v[200:201]
	v_lshlrev_b32_e32 v68, 16, v70
	v_and_b32_e32 v69, 0xffff0000, v70
	v_lshlrev_b32_e32 v70, 16, v71
	v_and_b32_e32 v71, 0xffff0000, v71
	v_pk_add_f32 v[58:59], v[58:59], v[70:71]
	v_pk_add_f32 v[56:57], v[56:57], v[68:69]
	s_nop 0
	v_cvt_pk_bf16_f32 v68, v56, v57
	v_cvt_pk_bf16_f32 v69, v58, v59
	v_mul_f32_e32 v57, v57, v57
	global_store_dwordx2 v[66:67], v[68:69], off offset:32
	v_mul_f32_e32 v59, v59, v59
	v_fmac_f32_e32 v57, v56, v56
	v_fmac_f32_e32 v59, v58, v58
	v_add_f32_e32 v56, v57, v59
	v_add_f32_e32 v56, v60, v56
	v_mov_b64_e32 v[70:71], v[202:203]
	v_lshlrev_b32_e32 v68, 16, v70
	v_and_b32_e32 v69, 0xffff0000, v70
	v_lshlrev_b32_e32 v70, 16, v71
	v_and_b32_e32 v71, 0xffff0000, v71
	v_pk_add_f32 v[54:55], v[54:55], v[70:71]
	v_pk_add_f32 v[52:53], v[52:53], v[68:69]
	s_nop 0
	v_cvt_pk_bf16_f32 v68, v52, v53
	v_cvt_pk_bf16_f32 v69, v54, v55
	v_mul_f32_e32 v53, v53, v53
	v_mul_f32_e32 v55, v55, v55
	v_fmac_f32_e32 v53, v52, v52
	v_fmac_f32_e32 v55, v54, v54
	v_add_f32_e32 v52, v53, v55
	v_add_f32_e32 v56, v56, v52
	global_store_dwordx2 v[66:67], v[68:69], off offset:256
	v_mov_b64_e32 v[70:71], v[204:205]
	v_lshlrev_b32_e32 v52, 16, v70
	v_and_b32_e32 v53, 0xffff0000, v70
	v_lshlrev_b32_e32 v54, 16, v71
	v_and_b32_e32 v55, 0xffff0000, v71
	v_pk_add_f32 v[50:51], v[50:51], v[54:55]
	v_pk_add_f32 v[52:53], v[48:49], v[52:53]
	v_mul_f32_e32 v49, v51, v51
	v_mul_f32_e32 v48, v53, v53
	v_fmac_f32_e32 v48, v52, v52
	v_fmac_f32_e32 v49, v50, v50
	v_add_f32_e32 v48, v48, v49
	v_add_f32_e32 v48, v56, v48
	ds_bpermute_b32 v49, v149, v48
	v_cvt_pk_bf16_f32 v52, v52, v53
	v_cvt_pk_bf16_f32 v53, v50, v51
	global_store_dwordx2 v[66:67], v[52:53], off offset:288
	s_waitcnt lgkmcnt(0)
	v_add_f32_e32 v48, v48, v49
	ds_bpermute_b32 v49, v153, v48
	s_and_saveexec_b64 s[24:25], s[8:9]
	s_cbranch_execz .LBB0_1837
	s_waitcnt lgkmcnt(0)
	v_add_f32_e32 v50, v48, v49
	v_lshlrev_b64 v[48:49], 6, v[64:65]
	v_lshl_add_u64 v[48:49], s[60:61], 0, v[48:49]
	v_lshl_add_u64 v[48:49], s[22:23], 2, v[48:49]
	s_lshl_b32 s10, s40, 2
	v_lshl_add_u64 v[48:49], v[48:49], 0, s[10:11]
	global_store_dword v[48:49], v50, off
.LBB0_1837:
	s_or_b64 exec, exec, s[24:25]
	v_add_u32_e32 v48, 0x90, v144
	s_waitcnt lgkmcnt(0)
	v_ashrrev_i32_e32 v49, 31, v48
	v_lshlrev_b64 v[50:51], 11, v[48:49]
	v_lshl_add_u64 v[50:51], s[62:63], 0, v[50:51]
	v_lshl_add_u64 v[50:51], v[142:143], 1, v[50:51]
	v_mov_b64_e32 v[52:53], v[206:207]
	v_lshlrev_b32_e32 v54, 16, v52
	v_and_b32_e32 v55, 0xffff0000, v52
	v_lshlrev_b32_e32 v52, 16, v53
	v_and_b32_e32 v53, 0xffff0000, v53
	v_pk_add_f32 v[46:47], v[46:47], v[52:53]
	v_pk_add_f32 v[44:45], v[44:45], v[54:55]
	s_nop 0
	v_cvt_pk_bf16_f32 v52, v44, v45
	v_cvt_pk_bf16_f32 v53, v46, v47
	v_mul_f32_e32 v45, v45, v45
	global_store_dwordx2 v[50:51], v[52:53], off
	v_mul_f32_e32 v47, v47, v47
	v_fmac_f32_e32 v45, v44, v44
	v_fmac_f32_e32 v47, v46, v46
	v_add_f32_e32 v44, v45, v47
	v_mov_b64_e32 v[54:55], v[208:209]
	v_lshlrev_b32_e32 v52, 16, v54
	v_and_b32_e32 v53, 0xffff0000, v54
	v_lshlrev_b32_e32 v54, 16, v55
	v_and_b32_e32 v55, 0xffff0000, v55
	v_pk_add_f32 v[42:43], v[42:43], v[54:55]
	v_pk_add_f32 v[40:41], v[40:41], v[52:53]
	s_nop 0
	v_cvt_pk_bf16_f32 v52, v40, v41
	v_cvt_pk_bf16_f32 v53, v42, v43
	v_mul_f32_e32 v41, v41, v41
	global_store_dwordx2 v[50:51], v[52:53], off offset:32
	v_mul_f32_e32 v43, v43, v43
	v_fmac_f32_e32 v41, v40, v40
	v_fmac_f32_e32 v43, v42, v42
	v_add_f32_e32 v40, v41, v43
	v_add_f32_e32 v40, v44, v40
	v_mov_b64_e32 v[54:55], v[210:211]
	v_lshlrev_b32_e32 v52, 16, v54
	v_and_b32_e32 v53, 0xffff0000, v54
	v_lshlrev_b32_e32 v54, 16, v55
	v_and_b32_e32 v55, 0xffff0000, v55
	v_pk_add_f32 v[38:39], v[38:39], v[54:55]
	v_pk_add_f32 v[36:37], v[36:37], v[52:53]
	s_nop 0
	v_cvt_pk_bf16_f32 v52, v36, v37
	v_cvt_pk_bf16_f32 v53, v38, v39
	v_mul_f32_e32 v37, v37, v37
	v_mul_f32_e32 v39, v39, v39
	v_fmac_f32_e32 v37, v36, v36
	v_fmac_f32_e32 v39, v38, v38
	v_add_f32_e32 v36, v37, v39
	v_add_f32_e32 v40, v40, v36
	global_store_dwordx2 v[50:51], v[52:53], off offset:256
	v_mov_b64_e32 v[54:55], v[212:213]
	v_lshlrev_b32_e32 v36, 16, v54
	v_and_b32_e32 v37, 0xffff0000, v54
	v_lshlrev_b32_e32 v38, 16, v55
	v_and_b32_e32 v39, 0xffff0000, v55
	v_pk_add_f32 v[34:35], v[34:35], v[38:39]
	v_pk_add_f32 v[36:37], v[32:33], v[36:37]
	v_mul_f32_e32 v33, v35, v35
	v_mul_f32_e32 v32, v37, v37
	v_fmac_f32_e32 v32, v36, v36
	v_fmac_f32_e32 v33, v34, v34
	v_add_f32_e32 v32, v32, v33
	v_add_f32_e32 v32, v40, v32
	ds_bpermute_b32 v33, v149, v32
	v_cvt_pk_bf16_f32 v36, v36, v37
	v_cvt_pk_bf16_f32 v37, v34, v35
	global_store_dwordx2 v[50:51], v[36:37], off offset:288
	s_waitcnt lgkmcnt(0)
	v_add_f32_e32 v32, v32, v33
	ds_bpermute_b32 v33, v153, v32
	s_and_saveexec_b64 s[24:25], s[8:9]
	s_cbranch_execz .LBB0_1839
	s_waitcnt lgkmcnt(0)
	v_add_f32_e32 v34, v32, v33
	v_lshlrev_b64 v[32:33], 6, v[48:49]
	v_lshl_add_u64 v[32:33], s[60:61], 0, v[32:33]
	v_lshl_add_u64 v[32:33], s[22:23], 2, v[32:33]
	s_lshl_b32 s10, s40, 2
	v_lshl_add_u64 v[32:33], v[32:33], 0, s[10:11]
	global_store_dword v[32:33], v34, off
.LBB0_1839:
	s_or_b64 exec, exec, s[24:25]
	v_add_u32_e32 v32, 0xa0, v144
	s_waitcnt lgkmcnt(0)
	v_ashrrev_i32_e32 v33, 31, v32
	v_lshlrev_b64 v[34:35], 11, v[32:33]
	v_lshl_add_u64 v[34:35], s[62:63], 0, v[34:35]
	v_lshl_add_u64 v[34:35], v[142:143], 1, v[34:35]
	v_mov_b64_e32 v[36:37], v[214:215]
	v_lshlrev_b32_e32 v38, 16, v36
	v_and_b32_e32 v39, 0xffff0000, v36
	v_lshlrev_b32_e32 v36, 16, v37
	v_and_b32_e32 v37, 0xffff0000, v37
	v_pk_add_f32 v[30:31], v[30:31], v[36:37]
	v_pk_add_f32 v[28:29], v[28:29], v[38:39]
	s_nop 0
	v_cvt_pk_bf16_f32 v36, v28, v29
	v_cvt_pk_bf16_f32 v37, v30, v31
	v_mul_f32_e32 v29, v29, v29
	global_store_dwordx2 v[34:35], v[36:37], off
	v_mul_f32_e32 v31, v31, v31
	v_fmac_f32_e32 v29, v28, v28
	v_fmac_f32_e32 v31, v30, v30
	v_add_f32_e32 v28, v29, v31
	v_mov_b64_e32 v[38:39], v[216:217]
	v_lshlrev_b32_e32 v36, 16, v38
	v_and_b32_e32 v37, 0xffff0000, v38
	v_lshlrev_b32_e32 v38, 16, v39
	v_and_b32_e32 v39, 0xffff0000, v39
	v_pk_add_f32 v[26:27], v[26:27], v[38:39]
	v_pk_add_f32 v[24:25], v[24:25], v[36:37]
	s_nop 0
	v_cvt_pk_bf16_f32 v36, v24, v25
	v_cvt_pk_bf16_f32 v37, v26, v27
	v_mul_f32_e32 v25, v25, v25
	global_store_dwordx2 v[34:35], v[36:37], off offset:32
	v_mul_f32_e32 v27, v27, v27
	v_fmac_f32_e32 v25, v24, v24
	v_fmac_f32_e32 v27, v26, v26
	v_add_f32_e32 v24, v25, v27
	v_add_f32_e32 v24, v28, v24
	v_mov_b64_e32 v[38:39], v[218:219]
	v_lshlrev_b32_e32 v36, 16, v38
	v_and_b32_e32 v37, 0xffff0000, v38
	v_lshlrev_b32_e32 v38, 16, v39
	v_and_b32_e32 v39, 0xffff0000, v39
	v_pk_add_f32 v[22:23], v[22:23], v[38:39]
	v_pk_add_f32 v[20:21], v[20:21], v[36:37]
	s_nop 0
	v_cvt_pk_bf16_f32 v36, v20, v21
	v_cvt_pk_bf16_f32 v37, v22, v23
	v_mul_f32_e32 v21, v21, v21
	v_mul_f32_e32 v23, v23, v23
	v_fmac_f32_e32 v21, v20, v20
	v_fmac_f32_e32 v23, v22, v22
	v_add_f32_e32 v20, v21, v23
	v_add_f32_e32 v24, v24, v20
	global_store_dwordx2 v[34:35], v[36:37], off offset:256
	v_mov_b64_e32 v[38:39], v[220:221]
	v_lshlrev_b32_e32 v20, 16, v38
	v_and_b32_e32 v21, 0xffff0000, v38
	v_lshlrev_b32_e32 v22, 16, v39
	v_and_b32_e32 v23, 0xffff0000, v39
	v_pk_add_f32 v[18:19], v[18:19], v[22:23]
	v_pk_add_f32 v[20:21], v[16:17], v[20:21]
	v_mul_f32_e32 v17, v19, v19
	v_mul_f32_e32 v16, v21, v21
	v_fmac_f32_e32 v16, v20, v20
	v_fmac_f32_e32 v17, v18, v18
	v_add_f32_e32 v16, v16, v17
	v_add_f32_e32 v16, v24, v16
	ds_bpermute_b32 v17, v149, v16
	v_cvt_pk_bf16_f32 v20, v20, v21
	v_cvt_pk_bf16_f32 v21, v18, v19
	global_store_dwordx2 v[34:35], v[20:21], off offset:288
	s_waitcnt lgkmcnt(0)
	v_add_f32_e32 v16, v16, v17
	ds_bpermute_b32 v17, v153, v16
	s_and_saveexec_b64 s[24:25], s[8:9]
	s_cbranch_execz .LBB0_1841
	s_waitcnt lgkmcnt(0)
	v_add_f32_e32 v18, v16, v17
	v_lshlrev_b64 v[16:17], 6, v[32:33]
	v_lshl_add_u64 v[16:17], s[60:61], 0, v[16:17]
	v_lshl_add_u64 v[16:17], s[22:23], 2, v[16:17]
	s_lshl_b32 s10, s40, 2
	v_lshl_add_u64 v[16:17], v[16:17], 0, s[10:11]
	global_store_dword v[16:17], v18, off
.LBB0_1841:
	s_or_b64 exec, exec, s[24:25]
	v_add_u32_e32 v16, 0xb0, v144
	s_waitcnt lgkmcnt(0)
	v_ashrrev_i32_e32 v17, 31, v16
	v_lshlrev_b64 v[18:19], 11, v[16:17]
	v_lshl_add_u64 v[18:19], s[62:63], 0, v[18:19]
	v_lshl_add_u64 v[18:19], v[142:143], 1, v[18:19]
	v_mov_b64_e32 v[20:21], v[222:223]
	v_lshlrev_b32_e32 v22, 16, v20
	v_and_b32_e32 v23, 0xffff0000, v20
	v_lshlrev_b32_e32 v20, 16, v21
	v_and_b32_e32 v21, 0xffff0000, v21
	v_pk_add_f32 v[14:15], v[14:15], v[20:21]
	v_pk_add_f32 v[12:13], v[12:13], v[22:23]
	s_nop 0
	v_cvt_pk_bf16_f32 v20, v12, v13
	v_cvt_pk_bf16_f32 v21, v14, v15
	v_mul_f32_e32 v13, v13, v13
	global_store_dwordx2 v[18:19], v[20:21], off
	v_mul_f32_e32 v15, v15, v15
	v_fmac_f32_e32 v13, v12, v12
	v_fmac_f32_e32 v15, v14, v14
	v_add_f32_e32 v12, v13, v15
	v_mov_b64_e32 v[22:23], v[224:225]
	v_lshlrev_b32_e32 v20, 16, v22
	v_and_b32_e32 v21, 0xffff0000, v22
	v_lshlrev_b32_e32 v22, 16, v23
	v_and_b32_e32 v23, 0xffff0000, v23
	v_pk_add_f32 v[10:11], v[10:11], v[22:23]
	v_pk_add_f32 v[8:9], v[8:9], v[20:21]
	s_nop 0
	v_cvt_pk_bf16_f32 v20, v8, v9
	v_cvt_pk_bf16_f32 v21, v10, v11
	v_mul_f32_e32 v9, v9, v9
	global_store_dwordx2 v[18:19], v[20:21], off offset:32
	v_mul_f32_e32 v11, v11, v11
	v_fmac_f32_e32 v9, v8, v8
	v_fmac_f32_e32 v11, v10, v10
	v_add_f32_e32 v8, v9, v11
	v_add_f32_e32 v8, v12, v8
	v_mov_b64_e32 v[22:23], v[226:227]
	v_lshlrev_b32_e32 v20, 16, v22
	v_and_b32_e32 v21, 0xffff0000, v22
	v_lshlrev_b32_e32 v22, 16, v23
	v_and_b32_e32 v23, 0xffff0000, v23
	v_pk_add_f32 v[6:7], v[6:7], v[22:23]
	v_pk_add_f32 v[4:5], v[4:5], v[20:21]
	s_nop 0
	v_cvt_pk_bf16_f32 v20, v4, v5
	v_cvt_pk_bf16_f32 v21, v6, v7
	v_mul_f32_e32 v5, v5, v5
	v_mul_f32_e32 v7, v7, v7
	v_fmac_f32_e32 v5, v4, v4
	v_fmac_f32_e32 v7, v6, v6
	v_add_f32_e32 v4, v5, v7
	v_add_f32_e32 v8, v8, v4
	global_store_dwordx2 v[18:19], v[20:21], off offset:256
	v_mov_b64_e32 v[22:23], v[228:229]
	v_lshlrev_b32_e32 v4, 16, v22
	v_and_b32_e32 v5, 0xffff0000, v22
	v_lshlrev_b32_e32 v6, 16, v23
	v_and_b32_e32 v7, 0xffff0000, v23
	v_pk_add_f32 v[2:3], v[2:3], v[6:7]
	v_pk_add_f32 v[4:5], v[0:1], v[4:5]
	v_mul_f32_e32 v1, v3, v3
	v_mul_f32_e32 v0, v5, v5
	v_fmac_f32_e32 v0, v4, v4
	v_fmac_f32_e32 v1, v2, v2
	v_add_f32_e32 v0, v0, v1
	v_add_f32_e32 v0, v8, v0
	ds_bpermute_b32 v1, v149, v0
	v_cvt_pk_bf16_f32 v4, v4, v5
	v_cvt_pk_bf16_f32 v5, v2, v3
	global_store_dwordx2 v[18:19], v[4:5], off offset:288
	s_waitcnt lgkmcnt(0)
	v_add_f32_e32 v0, v0, v1
	ds_bpermute_b32 v1, v153, v0
	s_and_saveexec_b64 s[24:25], s[8:9]
	s_cbranch_execz .LBB0_1843
	s_waitcnt lgkmcnt(0)
	v_add_f32_e32 v2, v0, v1
	v_lshlrev_b64 v[0:1], 6, v[16:17]
	v_lshl_add_u64 v[0:1], s[60:61], 0, v[0:1]
	v_lshl_add_u64 v[0:1], s[22:23], 2, v[0:1]
	s_lshl_b32 s10, s40, 2
	v_lshl_add_u64 v[0:1], v[0:1], 0, s[10:11]
	global_store_dword v[0:1], v2, off
